# v24 + one s_nop before the barrier of MMA blocks 1 and 3 so all four MFMA runs start 8-byte aligned (instruction fetch)
# baseline (speedup 1.0000x reference)
.LBB0_261:
	s_add_u32 s0, s76, 0xfff80080
	s_addc_u32 s1, s77, -1
	s_and_b64 s[84:85], s[84:85], exec
	s_cselect_b32 vcc_hi, s22, s1
	s_cselect_b32 vcc_lo, s23, s0
	s_cselect_b32 s85, s49, s58
	s_cselect_b32 s84, s57, s51
	s_add_i32 s0, 0, 0x10000
	s_add_i32 s1, 0, 0x14000
	v_add_u32_e32 v158, s0, v176
	v_add_u32_e32 v174, s1, v176
	ds_read_b128 v[146:149], v158
	ds_read_b128 v[150:153], v158 offset:1024
	ds_read_b128 v[154:157], v158 offset:2048
	ds_read_b128 v[158:161], v158 offset:3072
	ds_read_b128 v[162:165], v174
	ds_read_b128 v[166:169], v174 offset:1024
	ds_read_b128 v[170:173], v174 offset:2048
	ds_read_b128 v[178:181], v174 offset:3072
	s_add_i32 m0, s21, 0xc000
	ds_read_b128 v[182:185], v177
	ds_read_b128 v[186:189], v177 offset:1024
	ds_read_b128 v[190:193], v177 offset:2048
	ds_read_b128 v[204:207], v177 offset:3072
	ds_read_b128 v[208:211], v177 offset:4096
	ds_read_b128 v[212:215], v177 offset:5120
	ds_read_b128 v[216:219], v177 offset:6144
	ds_read_b128 v[220:223], v177 offset:7168
	global_load_lds_dwordx4 v138, s[76:77]
	s_add_i32 m0, s21, 0xe000
	s_nop 0
	global_load_lds_dwordx4 v140, s[76:77]
	s_waitcnt vmcnt(8)
	s_waitcnt lgkmcnt(0)
	s_nop 0
	s_barrier
	s_waitcnt lgkmcnt(0)
	v_mfma_f32_16x16x32_bf16 v[126:129], v[146:149], v[182:185], v[126:129]
	v_mfma_f32_16x16x32_bf16 v[126:129], v[150:153], v[186:189], v[126:129]
	v_mfma_f32_16x16x32_bf16 v[122:125], v[158:161], v[186:189], v[122:125]
	v_mfma_f32_16x16x32_bf16 v[122:125], v[154:157], v[182:185], v[122:125]
	v_mfma_f32_16x16x32_bf16 v[118:121], v[162:165], v[182:185], v[118:121]
	v_mfma_f32_16x16x32_bf16 v[118:121], v[166:169], v[186:189], v[118:121]
	v_mfma_f32_16x16x32_bf16 v[114:117], v[178:181], v[186:189], v[114:117]
	v_mfma_f32_16x16x32_bf16 v[114:117], v[170:173], v[182:185], v[114:117]
	v_mfma_f32_16x16x32_bf16 v[98:101], v[170:173], v[190:193], v[98:101]
	v_mfma_f32_16x16x32_bf16 v[98:101], v[178:181], v[204:207], v[98:101]
	v_mfma_f32_16x16x32_bf16 v[102:105], v[166:169], v[204:207], v[102:105]
	v_mfma_f32_16x16x32_bf16 v[102:105], v[162:165], v[190:193], v[102:105]
	v_mfma_f32_16x16x32_bf16 v[106:109], v[154:157], v[190:193], v[106:109]
	v_mfma_f32_16x16x32_bf16 v[106:109], v[158:161], v[204:207], v[106:109]
	v_mfma_f32_16x16x32_bf16 v[110:113], v[150:153], v[204:207], v[110:113]
	v_mfma_f32_16x16x32_bf16 v[110:113], v[146:149], v[190:193], v[110:113]
	v_mfma_f32_16x16x32_bf16 v[94:97], v[146:149], v[208:211], v[94:97]
	v_mfma_f32_16x16x32_bf16 v[94:97], v[150:153], v[212:215], v[94:97]
	v_mfma_f32_16x16x32_bf16 v[90:93], v[158:161], v[212:215], v[90:93]
	v_mfma_f32_16x16x32_bf16 v[90:93], v[154:157], v[208:211], v[90:93]
	v_mfma_f32_16x16x32_bf16 v[86:89], v[162:165], v[208:211], v[86:89]
	v_mfma_f32_16x16x32_bf16 v[86:89], v[166:169], v[212:215], v[86:89]
	v_mfma_f32_16x16x32_bf16 v[82:85], v[178:181], v[212:215], v[82:85]
	v_mfma_f32_16x16x32_bf16 v[82:85], v[170:173], v[208:211], v[82:85]
	v_mfma_f32_16x16x32_bf16 v[66:69], v[170:173], v[216:219], v[66:69]
	v_mfma_f32_16x16x32_bf16 v[66:69], v[178:181], v[220:223], v[66:69]
	v_mfma_f32_16x16x32_bf16 v[70:73], v[166:169], v[220:223], v[70:73]
	v_mfma_f32_16x16x32_bf16 v[70:73], v[162:165], v[216:219], v[70:73]
	v_mfma_f32_16x16x32_bf16 v[74:77], v[154:157], v[216:219], v[74:77]
	v_mfma_f32_16x16x32_bf16 v[74:77], v[158:161], v[220:223], v[74:77]
	v_mfma_f32_16x16x32_bf16 v[78:81], v[150:153], v[220:223], v[78:81]
	v_mfma_f32_16x16x32_bf16 v[78:81], v[146:149], v[216:219], v[78:81]
	s_barrier
	s_add_i32 s0, s0, s20
	s_mov_b32 m0, s0
	ds_read_b128 v[182:185], v177 offset:16384
	ds_read_b128 v[186:189], v177 offset:17408
	ds_read_b128 v[190:193], v177 offset:18432
	ds_read_b128 v[204:207], v177 offset:19456
	ds_read_b128 v[208:211], v177 offset:20480
	ds_read_b128 v[212:215], v177 offset:21504
	ds_read_b128 v[216:219], v177 offset:22528
	ds_read_b128 v[220:223], v177 offset:23552
	global_load_lds_dwordx4 v132, s[84:85]
	s_add_i32 m0, s0, 0x2000
	s_add_u32 s94, s84, 0x80000
	s_addc_u32 s95, s85, 0
	s_add_i32 s0, s1, s20
	global_load_lds_dwordx4 v130, s[84:85]
	s_mov_b32 m0, s0
	s_nop 0
	global_load_lds_dwordx4 v132, s[94:95]
	s_add_i32 m0, s0, 0x2000
	s_nop 0
	global_load_lds_dwordx4 v130, s[94:95]
	s_mov_b32 m0, s21
	s_nop 0
	global_load_lds_dwordx4 v132, vcc
	s_mov_b32 m0, s26
	s_nop 0
	global_load_lds_dwordx4 v130, vcc
	s_waitcnt vmcnt(8)
	s_waitcnt lgkmcnt(0)
	s_barrier
	s_waitcnt lgkmcnt(0)
	v_mfma_f32_16x16x32_bf16 v[62:65], v[146:149], v[182:185], v[62:65]
	v_mfma_f32_16x16x32_bf16 v[62:65], v[150:153], v[186:189], v[62:65]
	v_mfma_f32_16x16x32_bf16 v[58:61], v[158:161], v[186:189], v[58:61]
	v_mfma_f32_16x16x32_bf16 v[58:61], v[154:157], v[182:185], v[58:61]
	v_mfma_f32_16x16x32_bf16 v[54:57], v[162:165], v[182:185], v[54:57]
	v_mfma_f32_16x16x32_bf16 v[54:57], v[166:169], v[186:189], v[54:57]
	v_mfma_f32_16x16x32_bf16 v[50:53], v[178:181], v[186:189], v[50:53]
	v_mfma_f32_16x16x32_bf16 v[50:53], v[170:173], v[182:185], v[50:53]
	v_mfma_f32_16x16x32_bf16 v[34:37], v[170:173], v[190:193], v[34:37]
	v_mfma_f32_16x16x32_bf16 v[34:37], v[178:181], v[204:207], v[34:37]
	v_mfma_f32_16x16x32_bf16 v[38:41], v[166:169], v[204:207], v[38:41]
	v_mfma_f32_16x16x32_bf16 v[38:41], v[162:165], v[190:193], v[38:41]
	v_mfma_f32_16x16x32_bf16 v[42:45], v[154:157], v[190:193], v[42:45]
	v_mfma_f32_16x16x32_bf16 v[42:45], v[158:161], v[204:207], v[42:45]
	v_mfma_f32_16x16x32_bf16 v[46:49], v[150:153], v[204:207], v[46:49]
	v_mfma_f32_16x16x32_bf16 v[46:49], v[146:149], v[190:193], v[46:49]
	v_mfma_f32_16x16x32_bf16 v[30:33], v[146:149], v[208:211], v[30:33]
	v_mfma_f32_16x16x32_bf16 v[30:33], v[150:153], v[212:215], v[30:33]
	v_mfma_f32_16x16x32_bf16 v[26:29], v[158:161], v[212:215], v[26:29]
	v_mfma_f32_16x16x32_bf16 v[26:29], v[154:157], v[208:211], v[26:29]
	v_mfma_f32_16x16x32_bf16 v[22:25], v[162:165], v[208:211], v[22:25]
	v_mfma_f32_16x16x32_bf16 v[22:25], v[166:169], v[212:215], v[22:25]
	v_mfma_f32_16x16x32_bf16 v[18:21], v[178:181], v[212:215], v[18:21]
	v_mfma_f32_16x16x32_bf16 v[18:21], v[170:173], v[208:211], v[18:21]
	v_mfma_f32_16x16x32_bf16 v[2:5], v[170:173], v[216:219], v[2:5]
	v_mfma_f32_16x16x32_bf16 v[2:5], v[178:181], v[220:223], v[2:5]
	v_mfma_f32_16x16x32_bf16 v[6:9], v[166:169], v[220:223], v[6:9]
	v_mfma_f32_16x16x32_bf16 v[6:9], v[162:165], v[216:219], v[6:9]
	v_mfma_f32_16x16x32_bf16 v[10:13], v[154:157], v[216:219], v[10:13]
	v_mfma_f32_16x16x32_bf16 v[10:13], v[158:161], v[220:223], v[10:13]
	v_mfma_f32_16x16x32_bf16 v[14:17], v[150:153], v[220:223], v[14:17]
	v_mfma_f32_16x16x32_bf16 v[14:17], v[146:149], v[216:219], v[14:17]
	s_barrier
	s_add_i32 s0, 0, 0x18000
	s_add_i32 s1, 0, 0x1c000
	v_add_u32_e32 v158, s0, v176
	v_add_u32_e32 v178, s1, v176
	ds_read_b128 v[146:149], v158
	ds_read_b128 v[150:153], v158 offset:1024
	ds_read_b128 v[154:157], v158 offset:2048
	ds_read_b128 v[158:161], v158 offset:3072
	ds_read_b128 v[162:165], v178
	ds_read_b128 v[166:169], v178 offset:1024
	ds_read_b128 v[170:173], v178 offset:2048
	ds_read_b128 v[178:181], v178 offset:3072
	s_add_u32 s94, vcc_lo, 0x80000
	s_addc_u32 s95, vcc_hi, 0
	s_mov_b32 m0, s27
	ds_read_b128 v[182:185], v177 offset:32768
	ds_read_b128 v[186:189], v177 offset:33792
	ds_read_b128 v[190:193], v177 offset:34816
	ds_read_b128 v[204:207], v177 offset:35840
	ds_read_b128 v[208:211], v177 offset:36864
	ds_read_b128 v[212:215], v177 offset:37888
	ds_read_b128 v[216:219], v177 offset:38912
	ds_read_b128 v[220:223], v177 offset:39936
	global_load_lds_dwordx4 v132, s[94:95]
	s_mov_b32 m0, s29
	s_nop 0
	global_load_lds_dwordx4 v130, s[94:95]
	s_waitcnt vmcnt(8)
	s_waitcnt lgkmcnt(0)
	s_nop 0
	s_barrier
	s_waitcnt lgkmcnt(0)
	v_mfma_f32_16x16x32_bf16 v[126:129], v[146:149], v[182:185], v[126:129]
	v_mfma_f32_16x16x32_bf16 v[126:129], v[150:153], v[186:189], v[126:129]
	v_mfma_f32_16x16x32_bf16 v[122:125], v[158:161], v[186:189], v[122:125]
	v_mfma_f32_16x16x32_bf16 v[122:125], v[154:157], v[182:185], v[122:125]
	v_mfma_f32_16x16x32_bf16 v[118:121], v[162:165], v[182:185], v[118:121]
	v_mfma_f32_16x16x32_bf16 v[118:121], v[166:169], v[186:189], v[118:121]
	v_mfma_f32_16x16x32_bf16 v[114:117], v[178:181], v[186:189], v[114:117]
	v_mfma_f32_16x16x32_bf16 v[114:117], v[170:173], v[182:185], v[114:117]
	v_mfma_f32_16x16x32_bf16 v[98:101], v[170:173], v[190:193], v[98:101]
	v_mfma_f32_16x16x32_bf16 v[98:101], v[178:181], v[204:207], v[98:101]
	v_mfma_f32_16x16x32_bf16 v[102:105], v[166:169], v[204:207], v[102:105]
	v_mfma_f32_16x16x32_bf16 v[102:105], v[162:165], v[190:193], v[102:105]
	v_mfma_f32_16x16x32_bf16 v[106:109], v[154:157], v[190:193], v[106:109]
	v_mfma_f32_16x16x32_bf16 v[106:109], v[158:161], v[204:207], v[106:109]
	v_mfma_f32_16x16x32_bf16 v[110:113], v[150:153], v[204:207], v[110:113]
	v_mfma_f32_16x16x32_bf16 v[110:113], v[146:149], v[190:193], v[110:113]
	v_mfma_f32_16x16x32_bf16 v[94:97], v[146:149], v[208:211], v[94:97]
	v_mfma_f32_16x16x32_bf16 v[94:97], v[150:153], v[212:215], v[94:97]
	v_mfma_f32_16x16x32_bf16 v[90:93], v[158:161], v[212:215], v[90:93]
	v_mfma_f32_16x16x32_bf16 v[90:93], v[154:157], v[208:211], v[90:93]
	v_mfma_f32_16x16x32_bf16 v[86:89], v[162:165], v[208:211], v[86:89]
	v_mfma_f32_16x16x32_bf16 v[86:89], v[166:169], v[212:215], v[86:89]
	v_mfma_f32_16x16x32_bf16 v[82:85], v[178:181], v[212:215], v[82:85]
	v_mfma_f32_16x16x32_bf16 v[82:85], v[170:173], v[208:211], v[82:85]
	v_mfma_f32_16x16x32_bf16 v[66:69], v[170:173], v[216:219], v[66:69]
	v_mfma_f32_16x16x32_bf16 v[66:69], v[178:181], v[220:223], v[66:69]
	v_mfma_f32_16x16x32_bf16 v[70:73], v[166:169], v[220:223], v[70:73]
	v_mfma_f32_16x16x32_bf16 v[70:73], v[162:165], v[216:219], v[70:73]
	v_mfma_f32_16x16x32_bf16 v[74:77], v[154:157], v[216:219], v[74:77]
	v_mfma_f32_16x16x32_bf16 v[74:77], v[158:161], v[220:223], v[74:77]
	v_mfma_f32_16x16x32_bf16 v[78:81], v[150:153], v[220:223], v[78:81]
	v_mfma_f32_16x16x32_bf16 v[78:81], v[146:149], v[216:219], v[78:81]
	s_barrier
	s_add_u32 s98, s84, 0x80
	s_addc_u32 s99, s85, 0
	s_add_u32 s100, vcc_lo, 0x80
	s_addc_u32 s101, vcc_hi, 0
	s_add_i32 s0, s0, s20
	s_mov_b32 m0, s0
	ds_read_b128 v[182:185], v177 offset:49152
	ds_read_b128 v[186:189], v177 offset:50176
	ds_read_b128 v[190:193], v177 offset:51200
	ds_read_b128 v[204:207], v177 offset:52224
	ds_read_b128 v[208:211], v177 offset:53248
	ds_read_b128 v[212:215], v177 offset:54272
	ds_read_b128 v[216:219], v177 offset:55296
	ds_read_b128 v[220:223], v177 offset:56320
	global_load_lds_dwordx4 v132, s[98:99]
	s_add_i32 m0, s0, 0x2000
	s_add_u32 s84, s84, 0x80080
	s_addc_u32 s85, s85, 0
	s_add_i32 s0, s1, s20
	global_load_lds_dwordx4 v130, s[98:99]
	s_mov_b32 m0, s0
	s_nop 0
	global_load_lds_dwordx4 v132, s[84:85]
	s_add_i32 m0, s0, 0x2000
	s_nop 0
	global_load_lds_dwordx4 v130, s[84:85]
	s_mov_b32 m0, s40
	s_nop 0
	global_load_lds_dwordx4 v132, s[100:101]
	s_mov_b32 m0, s41
	s_nop 0
	global_load_lds_dwordx4 v130, s[100:101]
	s_waitcnt vmcnt(8)
	s_waitcnt lgkmcnt(0)
	s_barrier
	s_waitcnt lgkmcnt(0)
	v_mfma_f32_16x16x32_bf16 v[62:65], v[146:149], v[182:185], v[62:65]
	v_mfma_f32_16x16x32_bf16 v[62:65], v[150:153], v[186:189], v[62:65]
	v_mfma_f32_16x16x32_bf16 v[58:61], v[158:161], v[186:189], v[58:61]
	v_mfma_f32_16x16x32_bf16 v[58:61], v[154:157], v[182:185], v[58:61]
	v_mfma_f32_16x16x32_bf16 v[54:57], v[162:165], v[182:185], v[54:57]
	v_mfma_f32_16x16x32_bf16 v[54:57], v[166:169], v[186:189], v[54:57]
	v_mfma_f32_16x16x32_bf16 v[50:53], v[178:181], v[186:189], v[50:53]
	v_mfma_f32_16x16x32_bf16 v[50:53], v[170:173], v[182:185], v[50:53]
	v_mfma_f32_16x16x32_bf16 v[34:37], v[170:173], v[190:193], v[34:37]
	v_mfma_f32_16x16x32_bf16 v[34:37], v[178:181], v[204:207], v[34:37]
	v_mfma_f32_16x16x32_bf16 v[38:41], v[166:169], v[204:207], v[38:41]
	v_mfma_f32_16x16x32_bf16 v[38:41], v[162:165], v[190:193], v[38:41]
	v_mfma_f32_16x16x32_bf16 v[42:45], v[154:157], v[190:193], v[42:45]
	v_mfma_f32_16x16x32_bf16 v[42:45], v[158:161], v[204:207], v[42:45]
	v_mfma_f32_16x16x32_bf16 v[46:49], v[150:153], v[204:207], v[46:49]
	v_mfma_f32_16x16x32_bf16 v[46:49], v[146:149], v[190:193], v[46:49]
	v_mfma_f32_16x16x32_bf16 v[30:33], v[146:149], v[208:211], v[30:33]
	v_mfma_f32_16x16x32_bf16 v[30:33], v[150:153], v[212:215], v[30:33]
	v_mfma_f32_16x16x32_bf16 v[26:29], v[158:161], v[212:215], v[26:29]
	v_mfma_f32_16x16x32_bf16 v[26:29], v[154:157], v[208:211], v[26:29]
	v_mfma_f32_16x16x32_bf16 v[22:25], v[162:165], v[208:211], v[22:25]
	v_mfma_f32_16x16x32_bf16 v[22:25], v[166:169], v[212:215], v[22:25]
	v_mfma_f32_16x16x32_bf16 v[18:21], v[178:181], v[212:215], v[18:21]
	v_mfma_f32_16x16x32_bf16 v[18:21], v[170:173], v[208:211], v[18:21]
	v_mfma_f32_16x16x32_bf16 v[2:5], v[170:173], v[216:219], v[2:5]
	v_mfma_f32_16x16x32_bf16 v[2:5], v[178:181], v[220:223], v[2:5]
	v_mfma_f32_16x16x32_bf16 v[6:9], v[166:169], v[220:223], v[6:9]
	v_mfma_f32_16x16x32_bf16 v[6:9], v[162:165], v[216:219], v[6:9]
	v_mfma_f32_16x16x32_bf16 v[10:13], v[154:157], v[216:219], v[10:13]
	v_mfma_f32_16x16x32_bf16 v[10:13], v[158:161], v[220:223], v[10:13]
	v_mfma_f32_16x16x32_bf16 v[14:17], v[150:153], v[220:223], v[14:17]
	v_mfma_f32_16x16x32_bf16 v[14:17], v[146:149], v[216:219], v[14:17]
	s_barrier
	s_add_i32 s65, s65, 2
	s_add_u32 s76, s76, 0x100
	s_addc_u32 s77, s77, 0
	s_add_u32 s51, s51, 0x100
	s_addc_u32 s58, s58, 0
	s_cmp_gt_u32 s65, 29
	s_cbranch_scc1 .LBB0_264

.LBB0_285:
	s_add_u32 s0, s76, 0xfff80080
	s_addc_u32 s1, s77, -1
	s_and_b64 s[70:71], s[70:71], exec
	s_cselect_b32 vcc_hi, s21, s1
	s_cselect_b32 vcc_lo, s22, s0
	s_cselect_b32 s71, s23, s41
	s_cselect_b32 s70, s39, s7
	s_add_i32 s0, 0, 0x10000
	s_add_i32 s1, 0, 0x14000
	v_add_u32_e32 v146, s0, v1
	v_add_u32_e32 v174, s1, v1
	ds_read_b128 v[134:137], v146
	ds_read_b128 v[138:141], v146 offset:1024
	ds_read_b128 v[142:145], v146 offset:2048
	ds_read_b128 v[146:149], v146 offset:3072
	ds_read_b128 v[150:153], v174
	ds_read_b128 v[154:157], v174 offset:1024
	ds_read_b128 v[158:161], v174 offset:2048
	ds_read_b128 v[174:177], v174 offset:3072
	s_add_i32 m0, s67, 0xc000
	ds_read_b128 v[178:181], v222
	ds_read_b128 v[182:185], v222 offset:1024
	ds_read_b128 v[186:189], v222 offset:2048
	ds_read_b128 v[190:193], v222 offset:3072
	ds_read_b128 v[204:207], v222 offset:4096
	ds_read_b128 v[208:211], v222 offset:5120
	ds_read_b128 v[212:215], v222 offset:6144
	ds_read_b128 v[216:219], v222 offset:7168
	global_load_lds_dwordx4 v170, s[76:77]
	s_add_i32 m0, s67, 0xe000
	s_nop 0
	global_load_lds_dwordx4 v172, s[76:77]
	s_waitcnt vmcnt(8)
	s_waitcnt lgkmcnt(0)
	s_nop 0
	s_barrier
	s_waitcnt lgkmcnt(0)
	v_mfma_f32_16x16x32_bf16 v[126:129], v[134:137], v[178:181], v[126:129]
	v_mfma_f32_16x16x32_bf16 v[126:129], v[138:141], v[182:185], v[126:129]
	v_mfma_f32_16x16x32_bf16 v[122:125], v[146:149], v[182:185], v[122:125]
	v_mfma_f32_16x16x32_bf16 v[122:125], v[142:145], v[178:181], v[122:125]
	v_mfma_f32_16x16x32_bf16 v[118:121], v[150:153], v[178:181], v[118:121]
	v_mfma_f32_16x16x32_bf16 v[118:121], v[154:157], v[182:185], v[118:121]
	v_mfma_f32_16x16x32_bf16 v[114:117], v[174:177], v[182:185], v[114:117]
	v_mfma_f32_16x16x32_bf16 v[114:117], v[158:161], v[178:181], v[114:117]
	v_mfma_f32_16x16x32_bf16 v[98:101], v[158:161], v[186:189], v[98:101]
	v_mfma_f32_16x16x32_bf16 v[98:101], v[174:177], v[190:193], v[98:101]
	v_mfma_f32_16x16x32_bf16 v[102:105], v[154:157], v[190:193], v[102:105]
	v_mfma_f32_16x16x32_bf16 v[102:105], v[150:153], v[186:189], v[102:105]
	v_mfma_f32_16x16x32_bf16 v[106:109], v[142:145], v[186:189], v[106:109]
	v_mfma_f32_16x16x32_bf16 v[106:109], v[146:149], v[190:193], v[106:109]
	v_mfma_f32_16x16x32_bf16 v[110:113], v[138:141], v[190:193], v[110:113]
	v_mfma_f32_16x16x32_bf16 v[110:113], v[134:137], v[186:189], v[110:113]
	v_mfma_f32_16x16x32_bf16 v[94:97], v[134:137], v[204:207], v[94:97]
	v_mfma_f32_16x16x32_bf16 v[94:97], v[138:141], v[208:211], v[94:97]
	v_mfma_f32_16x16x32_bf16 v[90:93], v[146:149], v[208:211], v[90:93]
	v_mfma_f32_16x16x32_bf16 v[90:93], v[142:145], v[204:207], v[90:93]
	v_mfma_f32_16x16x32_bf16 v[86:89], v[150:153], v[204:207], v[86:89]
	v_mfma_f32_16x16x32_bf16 v[86:89], v[154:157], v[208:211], v[86:89]
	v_mfma_f32_16x16x32_bf16 v[82:85], v[174:177], v[208:211], v[82:85]
	v_mfma_f32_16x16x32_bf16 v[82:85], v[158:161], v[204:207], v[82:85]
	v_mfma_f32_16x16x32_bf16 v[66:69], v[158:161], v[212:215], v[66:69]
	v_mfma_f32_16x16x32_bf16 v[66:69], v[174:177], v[216:219], v[66:69]
	v_mfma_f32_16x16x32_bf16 v[70:73], v[154:157], v[216:219], v[70:73]
	v_mfma_f32_16x16x32_bf16 v[70:73], v[150:153], v[212:215], v[70:73]
	v_mfma_f32_16x16x32_bf16 v[74:77], v[142:145], v[212:215], v[74:77]
	v_mfma_f32_16x16x32_bf16 v[74:77], v[146:149], v[216:219], v[74:77]
	v_mfma_f32_16x16x32_bf16 v[78:81], v[138:141], v[216:219], v[78:81]
	v_mfma_f32_16x16x32_bf16 v[78:81], v[134:137], v[212:215], v[78:81]
	s_barrier
	s_add_i32 s0, s0, s54
	s_mov_b32 m0, s0
	ds_read_b128 v[178:181], v222 offset:16384
	ds_read_b128 v[182:185], v222 offset:17408
	ds_read_b128 v[186:189], v222 offset:18432
	ds_read_b128 v[190:193], v222 offset:19456
	ds_read_b128 v[204:207], v222 offset:20480
	ds_read_b128 v[208:211], v222 offset:21504
	ds_read_b128 v[212:215], v222 offset:22528
	ds_read_b128 v[216:219], v222 offset:23552
	global_load_lds_dwordx4 v164, s[70:71]
	s_add_i32 m0, s0, 0x2000
	s_add_u32 s44, s70, 0x80000
	s_addc_u32 s45, s71, 0
	s_add_i32 s0, s1, s54
	global_load_lds_dwordx4 v162, s[70:71]
	s_mov_b32 m0, s0
	s_nop 0
	global_load_lds_dwordx4 v164, s[44:45]
	s_add_i32 m0, s0, 0x2000
	s_nop 0
	global_load_lds_dwordx4 v162, s[44:45]
	s_mov_b32 m0, s67
	s_nop 0
	global_load_lds_dwordx4 v164, vcc
	s_mov_b32 m0, s68
	s_nop 0
	global_load_lds_dwordx4 v162, vcc
	s_waitcnt vmcnt(8)
	s_waitcnt lgkmcnt(0)
	s_barrier
	s_waitcnt lgkmcnt(0)
	v_mfma_f32_16x16x32_bf16 v[62:65], v[134:137], v[178:181], v[62:65]
	v_mfma_f32_16x16x32_bf16 v[62:65], v[138:141], v[182:185], v[62:65]
	v_mfma_f32_16x16x32_bf16 v[58:61], v[146:149], v[182:185], v[58:61]
	v_mfma_f32_16x16x32_bf16 v[58:61], v[142:145], v[178:181], v[58:61]
	v_mfma_f32_16x16x32_bf16 v[54:57], v[150:153], v[178:181], v[54:57]
	v_mfma_f32_16x16x32_bf16 v[54:57], v[154:157], v[182:185], v[54:57]
	v_mfma_f32_16x16x32_bf16 v[50:53], v[174:177], v[182:185], v[50:53]
	v_mfma_f32_16x16x32_bf16 v[50:53], v[158:161], v[178:181], v[50:53]
	v_mfma_f32_16x16x32_bf16 v[34:37], v[158:161], v[186:189], v[34:37]
	v_mfma_f32_16x16x32_bf16 v[34:37], v[174:177], v[190:193], v[34:37]
	v_mfma_f32_16x16x32_bf16 v[38:41], v[154:157], v[190:193], v[38:41]
	v_mfma_f32_16x16x32_bf16 v[38:41], v[150:153], v[186:189], v[38:41]
	v_mfma_f32_16x16x32_bf16 v[42:45], v[142:145], v[186:189], v[42:45]
	v_mfma_f32_16x16x32_bf16 v[42:45], v[146:149], v[190:193], v[42:45]
	v_mfma_f32_16x16x32_bf16 v[46:49], v[138:141], v[190:193], v[46:49]
	v_mfma_f32_16x16x32_bf16 v[46:49], v[134:137], v[186:189], v[46:49]
	v_mfma_f32_16x16x32_bf16 v[30:33], v[134:137], v[204:207], v[30:33]
	v_mfma_f32_16x16x32_bf16 v[30:33], v[138:141], v[208:211], v[30:33]
	v_mfma_f32_16x16x32_bf16 v[26:29], v[146:149], v[208:211], v[26:29]
	v_mfma_f32_16x16x32_bf16 v[26:29], v[142:145], v[204:207], v[26:29]
	v_mfma_f32_16x16x32_bf16 v[22:25], v[150:153], v[204:207], v[22:25]
	v_mfma_f32_16x16x32_bf16 v[22:25], v[154:157], v[208:211], v[22:25]
	v_mfma_f32_16x16x32_bf16 v[18:21], v[174:177], v[208:211], v[18:21]
	v_mfma_f32_16x16x32_bf16 v[18:21], v[158:161], v[204:207], v[18:21]
	v_mfma_f32_16x16x32_bf16 v[2:5], v[158:161], v[212:215], v[2:5]
	v_mfma_f32_16x16x32_bf16 v[2:5], v[174:177], v[216:219], v[2:5]
	v_mfma_f32_16x16x32_bf16 v[6:9], v[154:157], v[216:219], v[6:9]
	v_mfma_f32_16x16x32_bf16 v[6:9], v[150:153], v[212:215], v[6:9]
	v_mfma_f32_16x16x32_bf16 v[10:13], v[142:145], v[212:215], v[10:13]
	v_mfma_f32_16x16x32_bf16 v[10:13], v[146:149], v[216:219], v[10:13]
	v_mfma_f32_16x16x32_bf16 v[14:17], v[138:141], v[216:219], v[14:17]
	v_mfma_f32_16x16x32_bf16 v[14:17], v[134:137], v[212:215], v[14:17]
	s_barrier
	s_add_i32 s0, 0, 0x18000
	s_add_i32 s1, 0, 0x1c000
	v_add_u32_e32 v146, s0, v1
	v_add_u32_e32 v174, s1, v1
	ds_read_b128 v[134:137], v146
	ds_read_b128 v[138:141], v146 offset:1024
	ds_read_b128 v[142:145], v146 offset:2048
	ds_read_b128 v[146:149], v146 offset:3072
	ds_read_b128 v[150:153], v174
	ds_read_b128 v[154:157], v174 offset:1024
	ds_read_b128 v[158:161], v174 offset:2048
	ds_read_b128 v[174:177], v174 offset:3072
	s_add_u32 s44, vcc_lo, 0x80000
	s_addc_u32 s45, vcc_hi, 0
	s_mov_b32 m0, s8
	ds_read_b128 v[178:181], v222 offset:32768
	ds_read_b128 v[182:185], v222 offset:33792
	ds_read_b128 v[186:189], v222 offset:34816
	ds_read_b128 v[190:193], v222 offset:35840
	ds_read_b128 v[204:207], v222 offset:36864
	ds_read_b128 v[208:211], v222 offset:37888
	ds_read_b128 v[212:215], v222 offset:38912
	ds_read_b128 v[216:219], v222 offset:39936
	global_load_lds_dwordx4 v164, s[44:45]
	s_mov_b32 m0, s9
	s_nop 0
	global_load_lds_dwordx4 v162, s[44:45]
	s_waitcnt vmcnt(8)
	s_waitcnt lgkmcnt(0)
	s_nop 0
	s_barrier
	s_waitcnt lgkmcnt(0)
	v_mfma_f32_16x16x32_bf16 v[126:129], v[134:137], v[178:181], v[126:129]
	v_mfma_f32_16x16x32_bf16 v[126:129], v[138:141], v[182:185], v[126:129]
	v_mfma_f32_16x16x32_bf16 v[122:125], v[146:149], v[182:185], v[122:125]
	v_mfma_f32_16x16x32_bf16 v[122:125], v[142:145], v[178:181], v[122:125]
	v_mfma_f32_16x16x32_bf16 v[118:121], v[150:153], v[178:181], v[118:121]
	v_mfma_f32_16x16x32_bf16 v[118:121], v[154:157], v[182:185], v[118:121]
	v_mfma_f32_16x16x32_bf16 v[114:117], v[174:177], v[182:185], v[114:117]
	v_mfma_f32_16x16x32_bf16 v[114:117], v[158:161], v[178:181], v[114:117]
	v_mfma_f32_16x16x32_bf16 v[98:101], v[158:161], v[186:189], v[98:101]
	v_mfma_f32_16x16x32_bf16 v[98:101], v[174:177], v[190:193], v[98:101]
	v_mfma_f32_16x16x32_bf16 v[102:105], v[154:157], v[190:193], v[102:105]
	v_mfma_f32_16x16x32_bf16 v[102:105], v[150:153], v[186:189], v[102:105]
	v_mfma_f32_16x16x32_bf16 v[106:109], v[142:145], v[186:189], v[106:109]
	v_mfma_f32_16x16x32_bf16 v[106:109], v[146:149], v[190:193], v[106:109]
	v_mfma_f32_16x16x32_bf16 v[110:113], v[138:141], v[190:193], v[110:113]
	v_mfma_f32_16x16x32_bf16 v[110:113], v[134:137], v[186:189], v[110:113]
	v_mfma_f32_16x16x32_bf16 v[94:97], v[134:137], v[204:207], v[94:97]
	v_mfma_f32_16x16x32_bf16 v[94:97], v[138:141], v[208:211], v[94:97]
	v_mfma_f32_16x16x32_bf16 v[90:93], v[146:149], v[208:211], v[90:93]
	v_mfma_f32_16x16x32_bf16 v[90:93], v[142:145], v[204:207], v[90:93]
	v_mfma_f32_16x16x32_bf16 v[86:89], v[150:153], v[204:207], v[86:89]
	v_mfma_f32_16x16x32_bf16 v[86:89], v[154:157], v[208:211], v[86:89]
	v_mfma_f32_16x16x32_bf16 v[82:85], v[174:177], v[208:211], v[82:85]
	v_mfma_f32_16x16x32_bf16 v[82:85], v[158:161], v[204:207], v[82:85]
	v_mfma_f32_16x16x32_bf16 v[66:69], v[158:161], v[212:215], v[66:69]
	v_mfma_f32_16x16x32_bf16 v[66:69], v[174:177], v[216:219], v[66:69]
	v_mfma_f32_16x16x32_bf16 v[70:73], v[154:157], v[216:219], v[70:73]
	v_mfma_f32_16x16x32_bf16 v[70:73], v[150:153], v[212:215], v[70:73]
	v_mfma_f32_16x16x32_bf16 v[74:77], v[142:145], v[212:215], v[74:77]
	v_mfma_f32_16x16x32_bf16 v[74:77], v[146:149], v[216:219], v[74:77]
	v_mfma_f32_16x16x32_bf16 v[78:81], v[138:141], v[216:219], v[78:81]
	v_mfma_f32_16x16x32_bf16 v[78:81], v[134:137], v[212:215], v[78:81]
	s_barrier
	s_add_u32 s98, s70, 0x80
	s_addc_u32 s99, s71, 0
	s_add_u32 s100, vcc_lo, 0x80
	s_addc_u32 s101, vcc_hi, 0
	s_add_i32 s0, s0, s54
	s_mov_b32 m0, s0
	ds_read_b128 v[178:181], v222 offset:49152
	ds_read_b128 v[182:185], v222 offset:50176
	ds_read_b128 v[186:189], v222 offset:51200
	ds_read_b128 v[190:193], v222 offset:52224
	ds_read_b128 v[204:207], v222 offset:53248
	ds_read_b128 v[208:211], v222 offset:54272
	ds_read_b128 v[212:215], v222 offset:55296
	ds_read_b128 v[216:219], v222 offset:56320
	global_load_lds_dwordx4 v164, s[98:99]
	s_add_i32 m0, s0, 0x2000
	s_add_u32 s44, s70, 0x80080
	s_addc_u32 s45, s71, 0
	s_add_i32 s0, s1, s54
	global_load_lds_dwordx4 v162, s[98:99]
	s_mov_b32 m0, s0
	s_nop 0
	global_load_lds_dwordx4 v164, s[44:45]
	s_add_i32 m0, s0, 0x2000
	s_nop 0
	global_load_lds_dwordx4 v162, s[44:45]
	s_mov_b32 m0, s27
	s_nop 0
	global_load_lds_dwordx4 v164, s[100:101]
	s_mov_b32 m0, s26
	s_nop 0
	global_load_lds_dwordx4 v162, s[100:101]
	s_waitcnt vmcnt(8)
	s_waitcnt lgkmcnt(0)
	s_barrier
	s_waitcnt lgkmcnt(0)
	v_mfma_f32_16x16x32_bf16 v[62:65], v[134:137], v[178:181], v[62:65]
	v_mfma_f32_16x16x32_bf16 v[62:65], v[138:141], v[182:185], v[62:65]
	v_mfma_f32_16x16x32_bf16 v[58:61], v[146:149], v[182:185], v[58:61]
	v_mfma_f32_16x16x32_bf16 v[58:61], v[142:145], v[178:181], v[58:61]
	v_mfma_f32_16x16x32_bf16 v[54:57], v[150:153], v[178:181], v[54:57]
	v_mfma_f32_16x16x32_bf16 v[54:57], v[154:157], v[182:185], v[54:57]
	v_mfma_f32_16x16x32_bf16 v[50:53], v[174:177], v[182:185], v[50:53]
	v_mfma_f32_16x16x32_bf16 v[50:53], v[158:161], v[178:181], v[50:53]
	v_mfma_f32_16x16x32_bf16 v[34:37], v[158:161], v[186:189], v[34:37]
	v_mfma_f32_16x16x32_bf16 v[34:37], v[174:177], v[190:193], v[34:37]
	v_mfma_f32_16x16x32_bf16 v[38:41], v[154:157], v[190:193], v[38:41]
	v_mfma_f32_16x16x32_bf16 v[38:41], v[150:153], v[186:189], v[38:41]
	v_mfma_f32_16x16x32_bf16 v[42:45], v[142:145], v[186:189], v[42:45]
	v_mfma_f32_16x16x32_bf16 v[42:45], v[146:149], v[190:193], v[42:45]
	v_mfma_f32_16x16x32_bf16 v[46:49], v[138:141], v[190:193], v[46:49]
	v_mfma_f32_16x16x32_bf16 v[46:49], v[134:137], v[186:189], v[46:49]
	v_mfma_f32_16x16x32_bf16 v[30:33], v[134:137], v[204:207], v[30:33]
	v_mfma_f32_16x16x32_bf16 v[30:33], v[138:141], v[208:211], v[30:33]
	v_mfma_f32_16x16x32_bf16 v[26:29], v[146:149], v[208:211], v[26:29]
	v_mfma_f32_16x16x32_bf16 v[26:29], v[142:145], v[204:207], v[26:29]
	v_mfma_f32_16x16x32_bf16 v[22:25], v[150:153], v[204:207], v[22:25]
	v_mfma_f32_16x16x32_bf16 v[22:25], v[154:157], v[208:211], v[22:25]
	v_mfma_f32_16x16x32_bf16 v[18:21], v[174:177], v[208:211], v[18:21]
	v_mfma_f32_16x16x32_bf16 v[18:21], v[158:161], v[204:207], v[18:21]
	v_mfma_f32_16x16x32_bf16 v[2:5], v[158:161], v[212:215], v[2:5]
	v_mfma_f32_16x16x32_bf16 v[2:5], v[174:177], v[216:219], v[2:5]
	v_mfma_f32_16x16x32_bf16 v[6:9], v[154:157], v[216:219], v[6:9]
	v_mfma_f32_16x16x32_bf16 v[6:9], v[150:153], v[212:215], v[6:9]
	v_mfma_f32_16x16x32_bf16 v[10:13], v[142:145], v[212:215], v[10:13]
	v_mfma_f32_16x16x32_bf16 v[10:13], v[146:149], v[216:219], v[10:13]
	v_mfma_f32_16x16x32_bf16 v[14:17], v[138:141], v[216:219], v[14:17]
	v_mfma_f32_16x16x32_bf16 v[14:17], v[134:137], v[212:215], v[14:17]
	s_barrier
	s_add_i32 s43, s43, 2
	s_add_u32 s76, s76, 0x100
	s_addc_u32 s77, s77, 0
	s_add_u32 s7, s7, 0x100
	s_addc_u32 s41, s41, 0
	s_cmp_gt_u32 s43, 29
	s_cbranch_scc1 .LBB0_288

.LBB0_509:
	s_add_u32 s90, s76, 0x100
	s_addc_u32 s91, s77, 0
	s_and_b64 s[0:1], s[70:71], exec
	s_cselect_b32 vcc_hi, s22, s91
	s_cselect_b32 vcc_lo, s23, s90
	s_cselect_b32 s71, s41, s53
	s_cselect_b32 s70, s44, s51
	s_add_i32 s0, 0, 0x10000
	s_add_i32 s18, 0, 0x14000
	v_add_u32_e32 v114, s0, v1
	v_add_u32_e32 v154, s18, v1
	ds_read_b128 v[78:81], v114
	ds_read_b128 v[90:93], v114 offset:1024
	ds_read_b128 v[102:105], v114 offset:2048
	ds_read_b128 v[114:117], v114 offset:3072
	ds_read_b128 v[126:129], v154
	ds_read_b128 v[134:137], v154 offset:1024
	ds_read_b128 v[142:145], v154 offset:2048
	ds_read_b128 v[154:157], v154 offset:3072
	s_add_i32 m0, s29, 0xc000
	ds_read_b128 v[158:161], v237
	ds_read_b128 v[162:165], v237 offset:1024
	ds_read_b128 v[166:169], v237 offset:2048
	ds_read_b128 v[178:181], v237 offset:3072
	ds_read_b128 v[182:185], v237 offset:4096
	ds_read_b128 v[186:189], v237 offset:5120
	ds_read_b128 v[190:193], v237 offset:6144
	ds_read_b128 v[214:217], v237 offset:7168
	global_load_lds_dwordx4 v210, s[76:77]
	s_add_i32 m0, s29, 0xe000
	s_nop 0
	global_load_lds_dwordx4 v212, s[76:77]
	s_waitcnt vmcnt(8)
	s_waitcnt lgkmcnt(0)
	s_nop 0
	s_barrier
	s_waitcnt lgkmcnt(0)
	v_mfma_f32_16x16x32_bf16 v[174:177], v[78:81], v[158:161], v[174:177]
	v_mfma_f32_16x16x32_bf16 v[174:177], v[90:93], v[162:165], v[174:177]
	v_mfma_f32_16x16x32_bf16 v[170:173], v[114:117], v[162:165], v[170:173]
	v_mfma_f32_16x16x32_bf16 v[170:173], v[102:105], v[158:161], v[170:173]
	v_mfma_f32_16x16x32_bf16 v[150:153], v[126:129], v[158:161], v[150:153]
	v_mfma_f32_16x16x32_bf16 v[150:153], v[134:137], v[162:165], v[150:153]
	v_mfma_f32_16x16x32_bf16 v[146:149], v[154:157], v[162:165], v[146:149]
	v_mfma_f32_16x16x32_bf16 v[146:149], v[142:145], v[158:161], v[146:149]
	v_mfma_f32_16x16x32_bf16 v[118:121], v[142:145], v[166:169], v[118:121]
	v_mfma_f32_16x16x32_bf16 v[118:121], v[154:157], v[178:181], v[118:121]
	v_mfma_f32_16x16x32_bf16 v[122:125], v[134:137], v[178:181], v[122:125]
	v_mfma_f32_16x16x32_bf16 v[122:125], v[126:129], v[166:169], v[122:125]
	v_mfma_f32_16x16x32_bf16 v[130:133], v[102:105], v[166:169], v[130:133]
	v_mfma_f32_16x16x32_bf16 v[130:133], v[114:117], v[178:181], v[130:133]
	v_mfma_f32_16x16x32_bf16 v[138:141], v[90:93], v[178:181], v[138:141]
	v_mfma_f32_16x16x32_bf16 v[138:141], v[78:81], v[166:169], v[138:141]
	v_mfma_f32_16x16x32_bf16 v[110:113], v[78:81], v[182:185], v[110:113]
	v_mfma_f32_16x16x32_bf16 v[110:113], v[90:93], v[186:189], v[110:113]
	v_mfma_f32_16x16x32_bf16 v[106:109], v[114:117], v[186:189], v[106:109]
	v_mfma_f32_16x16x32_bf16 v[106:109], v[102:105], v[182:185], v[106:109]
	v_mfma_f32_16x16x32_bf16 v[98:101], v[126:129], v[182:185], v[98:101]
	v_mfma_f32_16x16x32_bf16 v[98:101], v[134:137], v[186:189], v[98:101]
	v_mfma_f32_16x16x32_bf16 v[94:97], v[154:157], v[186:189], v[94:97]
	v_mfma_f32_16x16x32_bf16 v[94:97], v[142:145], v[182:185], v[94:97]
	v_mfma_f32_16x16x32_bf16 v[66:69], v[142:145], v[190:193], v[66:69]
	v_mfma_f32_16x16x32_bf16 v[66:69], v[154:157], v[214:217], v[66:69]
	v_mfma_f32_16x16x32_bf16 v[74:77], v[134:137], v[214:217], v[74:77]
	v_mfma_f32_16x16x32_bf16 v[74:77], v[126:129], v[190:193], v[74:77]
	v_mfma_f32_16x16x32_bf16 v[82:85], v[102:105], v[190:193], v[82:85]
	v_mfma_f32_16x16x32_bf16 v[82:85], v[114:117], v[214:217], v[82:85]
	v_mfma_f32_16x16x32_bf16 v[86:89], v[90:93], v[214:217], v[86:89]
	v_mfma_f32_16x16x32_bf16 v[86:89], v[78:81], v[190:193], v[86:89]
	s_barrier
	s_add_i32 s0, s0, s28
	s_mov_b32 m0, s0
	ds_read_b128 v[158:161], v237 offset:16384
	ds_read_b128 v[162:165], v237 offset:17408
	ds_read_b128 v[166:169], v237 offset:18432
	ds_read_b128 v[178:181], v237 offset:19456
	ds_read_b128 v[182:185], v237 offset:20480
	ds_read_b128 v[186:189], v237 offset:21504
	ds_read_b128 v[190:193], v237 offset:22528
	ds_read_b128 v[214:217], v237 offset:23552
	global_load_lds_dwordx4 v194, s[70:71]
	s_add_i32 m0, s0, 0x2000
	s_add_u32 s0, s70, 0x80000
	s_addc_u32 s1, s71, 0
	s_add_i32 s18, s18, s28
	global_load_lds_dwordx4 v204, s[70:71]
	s_mov_b32 m0, s18
	s_nop 0
	global_load_lds_dwordx4 v194, s[0:1]
	s_add_i32 m0, s18, 0x2000
	s_nop 0
	global_load_lds_dwordx4 v204, s[0:1]
	s_mov_b32 m0, s29
	s_nop 0
	global_load_lds_dwordx4 v194, vcc
	s_mov_b32 m0, s31
	s_nop 0
	global_load_lds_dwordx4 v204, vcc
	s_waitcnt vmcnt(8)
	s_waitcnt lgkmcnt(0)
	s_barrier
	s_waitcnt lgkmcnt(0)
	v_mfma_f32_16x16x32_bf16 v[62:65], v[78:81], v[158:161], v[62:65]
	v_mfma_f32_16x16x32_bf16 v[62:65], v[90:93], v[162:165], v[62:65]
	v_mfma_f32_16x16x32_bf16 v[58:61], v[114:117], v[162:165], v[58:61]
	v_mfma_f32_16x16x32_bf16 v[58:61], v[102:105], v[158:161], v[58:61]
	v_mfma_f32_16x16x32_bf16 v[54:57], v[126:129], v[158:161], v[54:57]
	v_mfma_f32_16x16x32_bf16 v[54:57], v[134:137], v[162:165], v[54:57]
	v_mfma_f32_16x16x32_bf16 v[50:53], v[154:157], v[162:165], v[50:53]
	v_mfma_f32_16x16x32_bf16 v[50:53], v[142:145], v[158:161], v[50:53]
	v_mfma_f32_16x16x32_bf16 v[34:37], v[142:145], v[166:169], v[34:37]
	v_mfma_f32_16x16x32_bf16 v[34:37], v[154:157], v[178:181], v[34:37]
	v_mfma_f32_16x16x32_bf16 v[38:41], v[134:137], v[178:181], v[38:41]
	v_mfma_f32_16x16x32_bf16 v[38:41], v[126:129], v[166:169], v[38:41]
	v_mfma_f32_16x16x32_bf16 v[42:45], v[102:105], v[166:169], v[42:45]
	v_mfma_f32_16x16x32_bf16 v[42:45], v[114:117], v[178:181], v[42:45]
	v_mfma_f32_16x16x32_bf16 v[46:49], v[90:93], v[178:181], v[46:49]
	v_mfma_f32_16x16x32_bf16 v[46:49], v[78:81], v[166:169], v[46:49]
	v_mfma_f32_16x16x32_bf16 v[30:33], v[78:81], v[182:185], v[30:33]
	v_mfma_f32_16x16x32_bf16 v[30:33], v[90:93], v[186:189], v[30:33]
	v_mfma_f32_16x16x32_bf16 v[26:29], v[114:117], v[186:189], v[26:29]
	v_mfma_f32_16x16x32_bf16 v[26:29], v[102:105], v[182:185], v[26:29]
	v_mfma_f32_16x16x32_bf16 v[22:25], v[126:129], v[182:185], v[22:25]
	v_mfma_f32_16x16x32_bf16 v[22:25], v[134:137], v[186:189], v[22:25]
	v_mfma_f32_16x16x32_bf16 v[18:21], v[154:157], v[186:189], v[18:21]
	v_mfma_f32_16x16x32_bf16 v[18:21], v[142:145], v[182:185], v[18:21]
	v_mfma_f32_16x16x32_bf16 v[2:5], v[142:145], v[190:193], v[2:5]
	v_mfma_f32_16x16x32_bf16 v[2:5], v[154:157], v[214:217], v[2:5]
	v_mfma_f32_16x16x32_bf16 v[6:9], v[134:137], v[214:217], v[6:9]
	v_mfma_f32_16x16x32_bf16 v[6:9], v[126:129], v[190:193], v[6:9]
	v_mfma_f32_16x16x32_bf16 v[10:13], v[102:105], v[190:193], v[10:13]
	v_mfma_f32_16x16x32_bf16 v[10:13], v[114:117], v[214:217], v[10:13]
	v_mfma_f32_16x16x32_bf16 v[14:17], v[90:93], v[214:217], v[14:17]
	v_mfma_f32_16x16x32_bf16 v[14:17], v[78:81], v[190:193], v[14:17]
	s_barrier
	s_add_i32 s18, 0, 0x18000
	s_add_i32 s19, 0, 0x1c000
	v_add_u32_e32 v114, s18, v1
	v_add_u32_e32 v154, s19, v1
	ds_read_b128 v[78:81], v114
	ds_read_b128 v[90:93], v114 offset:1024
	ds_read_b128 v[102:105], v114 offset:2048
	ds_read_b128 v[114:117], v114 offset:3072
	ds_read_b128 v[126:129], v154
	ds_read_b128 v[134:137], v154 offset:1024
	ds_read_b128 v[142:145], v154 offset:2048
	ds_read_b128 v[154:157], v154 offset:3072
	s_add_u32 s0, vcc_lo, 0x80000
	s_addc_u32 s1, vcc_hi, 0
	s_mov_b32 m0, s33
	ds_read_b128 v[158:161], v237 offset:32768
	ds_read_b128 v[162:165], v237 offset:33792
	ds_read_b128 v[166:169], v237 offset:34816
	ds_read_b128 v[178:181], v237 offset:35840
	ds_read_b128 v[182:185], v237 offset:36864
	ds_read_b128 v[186:189], v237 offset:37888
	ds_read_b128 v[190:193], v237 offset:38912
	ds_read_b128 v[214:217], v237 offset:39936
	global_load_lds_dwordx4 v194, s[0:1]
	s_mov_b32 m0, s43
	s_nop 0
	global_load_lds_dwordx4 v204, s[0:1]
	s_waitcnt vmcnt(8)
	s_waitcnt lgkmcnt(0)
	s_nop 0
	s_barrier
	s_waitcnt lgkmcnt(0)
	v_mfma_f32_16x16x32_bf16 v[174:177], v[78:81], v[158:161], v[174:177]
	v_mfma_f32_16x16x32_bf16 v[174:177], v[90:93], v[162:165], v[174:177]
	v_mfma_f32_16x16x32_bf16 v[170:173], v[114:117], v[162:165], v[170:173]
	v_mfma_f32_16x16x32_bf16 v[170:173], v[102:105], v[158:161], v[170:173]
	v_mfma_f32_16x16x32_bf16 v[150:153], v[126:129], v[158:161], v[150:153]
	v_mfma_f32_16x16x32_bf16 v[150:153], v[134:137], v[162:165], v[150:153]
	v_mfma_f32_16x16x32_bf16 v[146:149], v[154:157], v[162:165], v[146:149]
	v_mfma_f32_16x16x32_bf16 v[146:149], v[142:145], v[158:161], v[146:149]
	v_mfma_f32_16x16x32_bf16 v[118:121], v[142:145], v[166:169], v[118:121]
	v_mfma_f32_16x16x32_bf16 v[118:121], v[154:157], v[178:181], v[118:121]
	v_mfma_f32_16x16x32_bf16 v[122:125], v[134:137], v[178:181], v[122:125]
	v_mfma_f32_16x16x32_bf16 v[122:125], v[126:129], v[166:169], v[122:125]
	v_mfma_f32_16x16x32_bf16 v[130:133], v[102:105], v[166:169], v[130:133]
	v_mfma_f32_16x16x32_bf16 v[130:133], v[114:117], v[178:181], v[130:133]
	v_mfma_f32_16x16x32_bf16 v[138:141], v[90:93], v[178:181], v[138:141]
	v_mfma_f32_16x16x32_bf16 v[138:141], v[78:81], v[166:169], v[138:141]
	v_mfma_f32_16x16x32_bf16 v[110:113], v[78:81], v[182:185], v[110:113]
	v_mfma_f32_16x16x32_bf16 v[110:113], v[90:93], v[186:189], v[110:113]
	v_mfma_f32_16x16x32_bf16 v[106:109], v[114:117], v[186:189], v[106:109]
	v_mfma_f32_16x16x32_bf16 v[106:109], v[102:105], v[182:185], v[106:109]
	v_mfma_f32_16x16x32_bf16 v[98:101], v[126:129], v[182:185], v[98:101]
	v_mfma_f32_16x16x32_bf16 v[98:101], v[134:137], v[186:189], v[98:101]
	v_mfma_f32_16x16x32_bf16 v[94:97], v[154:157], v[186:189], v[94:97]
	v_mfma_f32_16x16x32_bf16 v[94:97], v[142:145], v[182:185], v[94:97]
	v_mfma_f32_16x16x32_bf16 v[66:69], v[142:145], v[190:193], v[66:69]
	v_mfma_f32_16x16x32_bf16 v[66:69], v[154:157], v[214:217], v[66:69]
	v_mfma_f32_16x16x32_bf16 v[74:77], v[134:137], v[214:217], v[74:77]
	v_mfma_f32_16x16x32_bf16 v[74:77], v[126:129], v[190:193], v[74:77]
	v_mfma_f32_16x16x32_bf16 v[82:85], v[102:105], v[190:193], v[82:85]
	v_mfma_f32_16x16x32_bf16 v[82:85], v[114:117], v[214:217], v[82:85]
	v_mfma_f32_16x16x32_bf16 v[86:89], v[90:93], v[214:217], v[86:89]
	v_mfma_f32_16x16x32_bf16 v[86:89], v[78:81], v[190:193], v[86:89]
	s_barrier
	s_add_u32 s98, s70, 0x80
	s_addc_u32 s99, s71, 0
	s_add_u32 s100, vcc_lo, 0x80
	s_addc_u32 s101, vcc_hi, 0
	s_add_i32 s0, s18, s28
	s_mov_b32 m0, s0
	ds_read_b128 v[158:161], v237 offset:49152
	ds_read_b128 v[162:165], v237 offset:50176
	ds_read_b128 v[166:169], v237 offset:51200
	ds_read_b128 v[178:181], v237 offset:52224
	ds_read_b128 v[182:185], v237 offset:53248
	ds_read_b128 v[186:189], v237 offset:54272
	ds_read_b128 v[190:193], v237 offset:55296
	ds_read_b128 v[214:217], v237 offset:56320
	global_load_lds_dwordx4 v194, s[98:99]
	s_add_i32 m0, s0, 0x2000
	s_add_u32 s0, s70, 0x80080
	s_addc_u32 s1, s71, 0
	s_add_i32 s18, s19, s28
	global_load_lds_dwordx4 v204, s[98:99]
	s_mov_b32 m0, s18
	s_nop 0
	global_load_lds_dwordx4 v194, s[0:1]
	s_add_i32 m0, s18, 0x2000
	s_nop 0
	global_load_lds_dwordx4 v204, s[0:1]
	s_mov_b32 m0, s68
	s_nop 0
	global_load_lds_dwordx4 v194, s[100:101]
	s_mov_b32 m0, s79
	s_nop 0
	global_load_lds_dwordx4 v204, s[100:101]
	s_waitcnt vmcnt(8)
	s_waitcnt lgkmcnt(0)
	s_barrier
	s_waitcnt lgkmcnt(0)
	v_mfma_f32_16x16x32_bf16 v[62:65], v[78:81], v[158:161], v[62:65]
	v_mfma_f32_16x16x32_bf16 v[62:65], v[90:93], v[162:165], v[62:65]
	v_mfma_f32_16x16x32_bf16 v[58:61], v[114:117], v[162:165], v[58:61]
	v_mfma_f32_16x16x32_bf16 v[58:61], v[102:105], v[158:161], v[58:61]
	v_mfma_f32_16x16x32_bf16 v[54:57], v[126:129], v[158:161], v[54:57]
	v_mfma_f32_16x16x32_bf16 v[54:57], v[134:137], v[162:165], v[54:57]
	v_mfma_f32_16x16x32_bf16 v[50:53], v[154:157], v[162:165], v[50:53]
	v_mfma_f32_16x16x32_bf16 v[50:53], v[142:145], v[158:161], v[50:53]
	v_mfma_f32_16x16x32_bf16 v[34:37], v[142:145], v[166:169], v[34:37]
	v_mfma_f32_16x16x32_bf16 v[34:37], v[154:157], v[178:181], v[34:37]
	v_mfma_f32_16x16x32_bf16 v[38:41], v[134:137], v[178:181], v[38:41]
	v_mfma_f32_16x16x32_bf16 v[38:41], v[126:129], v[166:169], v[38:41]
	v_mfma_f32_16x16x32_bf16 v[42:45], v[102:105], v[166:169], v[42:45]
	v_mfma_f32_16x16x32_bf16 v[42:45], v[114:117], v[178:181], v[42:45]
	v_mfma_f32_16x16x32_bf16 v[46:49], v[90:93], v[178:181], v[46:49]
	v_mfma_f32_16x16x32_bf16 v[46:49], v[78:81], v[166:169], v[46:49]
	v_mfma_f32_16x16x32_bf16 v[30:33], v[78:81], v[182:185], v[30:33]
	v_mfma_f32_16x16x32_bf16 v[30:33], v[90:93], v[186:189], v[30:33]
	v_mfma_f32_16x16x32_bf16 v[26:29], v[114:117], v[186:189], v[26:29]
	v_mfma_f32_16x16x32_bf16 v[26:29], v[102:105], v[182:185], v[26:29]
	v_mfma_f32_16x16x32_bf16 v[22:25], v[126:129], v[182:185], v[22:25]
	v_mfma_f32_16x16x32_bf16 v[22:25], v[134:137], v[186:189], v[22:25]
	v_mfma_f32_16x16x32_bf16 v[18:21], v[154:157], v[186:189], v[18:21]
	v_mfma_f32_16x16x32_bf16 v[18:21], v[142:145], v[182:185], v[18:21]
	v_mfma_f32_16x16x32_bf16 v[2:5], v[142:145], v[190:193], v[2:5]
	v_mfma_f32_16x16x32_bf16 v[2:5], v[154:157], v[214:217], v[2:5]
	v_mfma_f32_16x16x32_bf16 v[6:9], v[134:137], v[214:217], v[6:9]
	v_mfma_f32_16x16x32_bf16 v[6:9], v[126:129], v[190:193], v[6:9]
	v_mfma_f32_16x16x32_bf16 v[10:13], v[102:105], v[190:193], v[10:13]
	v_mfma_f32_16x16x32_bf16 v[10:13], v[114:117], v[214:217], v[10:13]
	v_mfma_f32_16x16x32_bf16 v[14:17], v[90:93], v[214:217], v[14:17]
	v_mfma_f32_16x16x32_bf16 v[14:17], v[78:81], v[190:193], v[14:17]
	s_barrier
	s_add_i32 s57, s57, 2
	s_add_u32 s51, s51, 0x100
	s_addc_u32 s53, s53, 0
	s_cmp_gt_u32 s57, 29
	s_mov_b64 s[76:77], s[90:91]
	s_cbranch_scc1 .LBB0_512

.LBB0_581:
	s_add_u32 s18, s62, 0xfff80080
	s_addc_u32 s19, s63, -1
	s_and_b64 s[0:1], s[64:65], exec
	s_cselect_b32 s71, s22, s19
	s_cselect_b32 s70, s23, s18
	s_cselect_b32 s65, s39, s58
	s_cselect_b32 s64, s47, s53
	s_add_i32 s0, 0, 0x10000
	v_add_u32_e32 v153, s0, v1
	s_add_i32 s18, 0, 0x14000
	ds_read_b128 v[144:147], v153
	ds_read_b128 v[148:151], v153 offset:1024
	ds_read_b128 v[154:157], v153 offset:2048
	ds_read_b128 v[158:161], v153 offset:3072
	v_add_u32_e32 v153, s18, v1
	ds_read_b128 v[162:165], v153
	ds_read_b128 v[166:169], v153 offset:1024
	ds_read_b128 v[170:173], v153 offset:2048
	ds_read_b128 v[174:177], v153 offset:3072
	s_add_i32 m0, s29, 0xc000
	ds_read_b128 v[178:181], v152
	ds_read_b128 v[182:185], v152 offset:1024
	ds_read_b128 v[186:189], v152 offset:2048
	ds_read_b128 v[190:193], v152 offset:3072
	ds_read_b128 v[204:207], v152 offset:4096
	ds_read_b128 v[208:211], v152 offset:5120
	ds_read_b128 v[212:215], v152 offset:6144
	ds_read_b128 v[216:219], v152 offset:7168
	global_load_lds_dwordx4 v136, s[62:63]
	s_add_i32 m0, s29, 0xe000
	s_nop 0
	global_load_lds_dwordx4 v138, s[62:63]
	s_waitcnt vmcnt(8)
	s_waitcnt lgkmcnt(0)
	s_nop 0
	s_barrier
	s_waitcnt lgkmcnt(0)
	v_mfma_f32_16x16x32_bf16 v[126:129], v[144:147], v[178:181], v[126:129]
	v_mfma_f32_16x16x32_bf16 v[126:129], v[148:151], v[182:185], v[126:129]
	v_mfma_f32_16x16x32_bf16 v[122:125], v[158:161], v[182:185], v[122:125]
	v_mfma_f32_16x16x32_bf16 v[122:125], v[154:157], v[178:181], v[122:125]
	v_mfma_f32_16x16x32_bf16 v[118:121], v[162:165], v[178:181], v[118:121]
	v_mfma_f32_16x16x32_bf16 v[118:121], v[166:169], v[182:185], v[118:121]
	v_mfma_f32_16x16x32_bf16 v[114:117], v[174:177], v[182:185], v[114:117]
	v_mfma_f32_16x16x32_bf16 v[114:117], v[170:173], v[178:181], v[114:117]
	v_mfma_f32_16x16x32_bf16 v[98:101], v[170:173], v[186:189], v[98:101]
	v_mfma_f32_16x16x32_bf16 v[98:101], v[174:177], v[190:193], v[98:101]
	v_mfma_f32_16x16x32_bf16 v[102:105], v[166:169], v[190:193], v[102:105]
	v_mfma_f32_16x16x32_bf16 v[102:105], v[162:165], v[186:189], v[102:105]
	v_mfma_f32_16x16x32_bf16 v[106:109], v[154:157], v[186:189], v[106:109]
	v_mfma_f32_16x16x32_bf16 v[106:109], v[158:161], v[190:193], v[106:109]
	v_mfma_f32_16x16x32_bf16 v[110:113], v[148:151], v[190:193], v[110:113]
	v_mfma_f32_16x16x32_bf16 v[110:113], v[144:147], v[186:189], v[110:113]
	v_mfma_f32_16x16x32_bf16 v[94:97], v[144:147], v[204:207], v[94:97]
	v_mfma_f32_16x16x32_bf16 v[94:97], v[148:151], v[208:211], v[94:97]
	v_mfma_f32_16x16x32_bf16 v[90:93], v[158:161], v[208:211], v[90:93]
	v_mfma_f32_16x16x32_bf16 v[90:93], v[154:157], v[204:207], v[90:93]
	v_mfma_f32_16x16x32_bf16 v[86:89], v[162:165], v[204:207], v[86:89]
	v_mfma_f32_16x16x32_bf16 v[86:89], v[166:169], v[208:211], v[86:89]
	v_mfma_f32_16x16x32_bf16 v[82:85], v[174:177], v[208:211], v[82:85]
	v_mfma_f32_16x16x32_bf16 v[82:85], v[170:173], v[204:207], v[82:85]
	v_mfma_f32_16x16x32_bf16 v[66:69], v[170:173], v[212:215], v[66:69]
	v_mfma_f32_16x16x32_bf16 v[66:69], v[174:177], v[216:219], v[66:69]
	v_mfma_f32_16x16x32_bf16 v[70:73], v[166:169], v[216:219], v[70:73]
	v_mfma_f32_16x16x32_bf16 v[70:73], v[162:165], v[212:215], v[70:73]
	v_mfma_f32_16x16x32_bf16 v[74:77], v[154:157], v[212:215], v[74:77]
	v_mfma_f32_16x16x32_bf16 v[74:77], v[158:161], v[216:219], v[74:77]
	v_mfma_f32_16x16x32_bf16 v[78:81], v[148:151], v[216:219], v[78:81]
	v_mfma_f32_16x16x32_bf16 v[78:81], v[144:147], v[212:215], v[78:81]
	s_barrier
	s_add_i32 s0, s0, s28
	s_mov_b32 m0, s0
	ds_read_b128 v[178:181], v152 offset:16384
	ds_read_b128 v[182:185], v152 offset:17408
	ds_read_b128 v[186:189], v152 offset:18432
	ds_read_b128 v[190:193], v152 offset:19456
	ds_read_b128 v[204:207], v152 offset:20480
	ds_read_b128 v[208:211], v152 offset:21504
	ds_read_b128 v[212:215], v152 offset:22528
	ds_read_b128 v[216:219], v152 offset:23552
	global_load_lds_dwordx4 v194, s[64:65]
	s_add_i32 m0, s0, 0x2000
	s_add_u32 s0, s64, 0x80000
	s_addc_u32 s1, s65, 0
	s_add_i32 s18, s18, s28
	global_load_lds_dwordx4 v130, s[64:65]
	s_mov_b32 m0, s18
	s_nop 0
	global_load_lds_dwordx4 v194, s[0:1]
	s_add_i32 m0, s18, 0x2000
	s_nop 0
	global_load_lds_dwordx4 v130, s[0:1]
	s_mov_b32 m0, s29
	s_nop 0
	global_load_lds_dwordx4 v194, s[70:71]
	s_mov_b32 m0, s31
	s_nop 0
	global_load_lds_dwordx4 v130, s[70:71]
	s_waitcnt vmcnt(8)
	s_waitcnt lgkmcnt(0)
	s_barrier
	s_waitcnt lgkmcnt(0)
	v_mfma_f32_16x16x32_bf16 v[62:65], v[144:147], v[178:181], v[62:65]
	v_mfma_f32_16x16x32_bf16 v[62:65], v[148:151], v[182:185], v[62:65]
	v_mfma_f32_16x16x32_bf16 v[58:61], v[158:161], v[182:185], v[58:61]
	v_mfma_f32_16x16x32_bf16 v[58:61], v[154:157], v[178:181], v[58:61]
	v_mfma_f32_16x16x32_bf16 v[54:57], v[162:165], v[178:181], v[54:57]
	v_mfma_f32_16x16x32_bf16 v[54:57], v[166:169], v[182:185], v[54:57]
	v_mfma_f32_16x16x32_bf16 v[50:53], v[174:177], v[182:185], v[50:53]
	v_mfma_f32_16x16x32_bf16 v[50:53], v[170:173], v[178:181], v[50:53]
	v_mfma_f32_16x16x32_bf16 v[34:37], v[170:173], v[186:189], v[34:37]
	v_mfma_f32_16x16x32_bf16 v[34:37], v[174:177], v[190:193], v[34:37]
	v_mfma_f32_16x16x32_bf16 v[38:41], v[166:169], v[190:193], v[38:41]
	v_mfma_f32_16x16x32_bf16 v[38:41], v[162:165], v[186:189], v[38:41]
	v_mfma_f32_16x16x32_bf16 v[42:45], v[154:157], v[186:189], v[42:45]
	v_mfma_f32_16x16x32_bf16 v[42:45], v[158:161], v[190:193], v[42:45]
	v_mfma_f32_16x16x32_bf16 v[46:49], v[148:151], v[190:193], v[46:49]
	v_mfma_f32_16x16x32_bf16 v[46:49], v[144:147], v[186:189], v[46:49]
	v_mfma_f32_16x16x32_bf16 v[30:33], v[144:147], v[204:207], v[30:33]
	v_mfma_f32_16x16x32_bf16 v[30:33], v[148:151], v[208:211], v[30:33]
	v_mfma_f32_16x16x32_bf16 v[26:29], v[158:161], v[208:211], v[26:29]
	v_mfma_f32_16x16x32_bf16 v[26:29], v[154:157], v[204:207], v[26:29]
	v_mfma_f32_16x16x32_bf16 v[22:25], v[162:165], v[204:207], v[22:25]
	v_mfma_f32_16x16x32_bf16 v[22:25], v[166:169], v[208:211], v[22:25]
	v_mfma_f32_16x16x32_bf16 v[18:21], v[174:177], v[208:211], v[18:21]
	v_mfma_f32_16x16x32_bf16 v[18:21], v[170:173], v[204:207], v[18:21]
	v_mfma_f32_16x16x32_bf16 v[2:5], v[170:173], v[212:215], v[2:5]
	v_mfma_f32_16x16x32_bf16 v[2:5], v[174:177], v[216:219], v[2:5]
	v_mfma_f32_16x16x32_bf16 v[6:9], v[166:169], v[216:219], v[6:9]
	v_mfma_f32_16x16x32_bf16 v[6:9], v[162:165], v[212:215], v[6:9]
	v_mfma_f32_16x16x32_bf16 v[10:13], v[154:157], v[212:215], v[10:13]
	v_mfma_f32_16x16x32_bf16 v[10:13], v[158:161], v[216:219], v[10:13]
	v_mfma_f32_16x16x32_bf16 v[14:17], v[148:151], v[216:219], v[14:17]
	v_mfma_f32_16x16x32_bf16 v[14:17], v[144:147], v[212:215], v[14:17]
	s_barrier
	s_add_i32 s18, 0, 0x18000
	v_add_u32_e32 v153, s18, v1
	s_add_i32 s19, 0, 0x1c000
	ds_read_b128 v[144:147], v153
	ds_read_b128 v[148:151], v153 offset:1024
	ds_read_b128 v[154:157], v153 offset:2048
	ds_read_b128 v[158:161], v153 offset:3072
	v_add_u32_e32 v153, s19, v1
	ds_read_b128 v[162:165], v153
	ds_read_b128 v[166:169], v153 offset:1024
	ds_read_b128 v[170:173], v153 offset:2048
	ds_read_b128 v[174:177], v153 offset:3072
	s_add_u32 s0, s70, 0x80000
	s_addc_u32 s1, s71, 0
	s_mov_b32 m0, s33
	ds_read_b128 v[178:181], v152 offset:32768
	ds_read_b128 v[182:185], v152 offset:33792
	ds_read_b128 v[186:189], v152 offset:34816
	ds_read_b128 v[190:193], v152 offset:35840
	ds_read_b128 v[204:207], v152 offset:36864
	ds_read_b128 v[208:211], v152 offset:37888
	ds_read_b128 v[212:215], v152 offset:38912
	ds_read_b128 v[216:219], v152 offset:39936
	global_load_lds_dwordx4 v194, s[0:1]
	s_mov_b32 m0, s40
	s_nop 0
	global_load_lds_dwordx4 v130, s[0:1]
	s_waitcnt vmcnt(8)
	s_waitcnt lgkmcnt(0)
	s_nop 0
	s_barrier
	s_waitcnt lgkmcnt(0)
	v_mfma_f32_16x16x32_bf16 v[126:129], v[144:147], v[178:181], v[126:129]
	v_mfma_f32_16x16x32_bf16 v[126:129], v[148:151], v[182:185], v[126:129]
	v_mfma_f32_16x16x32_bf16 v[122:125], v[158:161], v[182:185], v[122:125]
	v_mfma_f32_16x16x32_bf16 v[122:125], v[154:157], v[178:181], v[122:125]
	v_mfma_f32_16x16x32_bf16 v[118:121], v[162:165], v[178:181], v[118:121]
	v_mfma_f32_16x16x32_bf16 v[118:121], v[166:169], v[182:185], v[118:121]
	v_mfma_f32_16x16x32_bf16 v[114:117], v[174:177], v[182:185], v[114:117]
	v_mfma_f32_16x16x32_bf16 v[114:117], v[170:173], v[178:181], v[114:117]
	v_mfma_f32_16x16x32_bf16 v[98:101], v[170:173], v[186:189], v[98:101]
	v_mfma_f32_16x16x32_bf16 v[98:101], v[174:177], v[190:193], v[98:101]
	v_mfma_f32_16x16x32_bf16 v[102:105], v[166:169], v[190:193], v[102:105]
	v_mfma_f32_16x16x32_bf16 v[102:105], v[162:165], v[186:189], v[102:105]
	v_mfma_f32_16x16x32_bf16 v[106:109], v[154:157], v[186:189], v[106:109]
	v_mfma_f32_16x16x32_bf16 v[106:109], v[158:161], v[190:193], v[106:109]
	v_mfma_f32_16x16x32_bf16 v[110:113], v[148:151], v[190:193], v[110:113]
	v_mfma_f32_16x16x32_bf16 v[110:113], v[144:147], v[186:189], v[110:113]
	v_mfma_f32_16x16x32_bf16 v[94:97], v[144:147], v[204:207], v[94:97]
	v_mfma_f32_16x16x32_bf16 v[94:97], v[148:151], v[208:211], v[94:97]
	v_mfma_f32_16x16x32_bf16 v[90:93], v[158:161], v[208:211], v[90:93]
	v_mfma_f32_16x16x32_bf16 v[90:93], v[154:157], v[204:207], v[90:93]
	v_mfma_f32_16x16x32_bf16 v[86:89], v[162:165], v[204:207], v[86:89]
	v_mfma_f32_16x16x32_bf16 v[86:89], v[166:169], v[208:211], v[86:89]
	v_mfma_f32_16x16x32_bf16 v[82:85], v[174:177], v[208:211], v[82:85]
	v_mfma_f32_16x16x32_bf16 v[82:85], v[170:173], v[204:207], v[82:85]
	v_mfma_f32_16x16x32_bf16 v[66:69], v[170:173], v[212:215], v[66:69]
	v_mfma_f32_16x16x32_bf16 v[66:69], v[174:177], v[216:219], v[66:69]
	v_mfma_f32_16x16x32_bf16 v[70:73], v[166:169], v[216:219], v[70:73]
	v_mfma_f32_16x16x32_bf16 v[70:73], v[162:165], v[212:215], v[70:73]
	v_mfma_f32_16x16x32_bf16 v[74:77], v[154:157], v[212:215], v[74:77]
	v_mfma_f32_16x16x32_bf16 v[74:77], v[158:161], v[216:219], v[74:77]
	v_mfma_f32_16x16x32_bf16 v[78:81], v[148:151], v[216:219], v[78:81]
	v_mfma_f32_16x16x32_bf16 v[78:81], v[144:147], v[212:215], v[78:81]
	s_barrier
	s_add_u32 s98, s64, 0x80
	s_addc_u32 s99, s65, 0
	s_add_u32 s100, s70, 0x80
	s_addc_u32 s101, s71, 0
	s_add_i32 s0, s18, s28
	s_mov_b32 m0, s0
	ds_read_b128 v[178:181], v152 offset:49152
	ds_read_b128 v[182:185], v152 offset:50176
	ds_read_b128 v[186:189], v152 offset:51200
	ds_read_b128 v[190:193], v152 offset:52224
	ds_read_b128 v[204:207], v152 offset:53248
	ds_read_b128 v[208:211], v152 offset:54272
	ds_read_b128 v[212:215], v152 offset:55296
	ds_read_b128 v[216:219], v152 offset:56320
	global_load_lds_dwordx4 v194, s[98:99]
	s_add_i32 m0, s0, 0x2000
	s_add_u32 s0, s64, 0x80080
	s_addc_u32 s1, s65, 0
	s_add_i32 s18, s19, s28
	global_load_lds_dwordx4 v130, s[98:99]
	s_mov_b32 m0, s18
	s_nop 0
	global_load_lds_dwordx4 v194, s[0:1]
	s_add_i32 m0, s18, 0x2000
	s_nop 0
	global_load_lds_dwordx4 v130, s[0:1]
	s_mov_b32 m0, s54
	s_nop 0
	global_load_lds_dwordx4 v194, s[100:101]
	s_mov_b32 m0, s57
	s_nop 0
	global_load_lds_dwordx4 v130, s[100:101]
	s_waitcnt vmcnt(8)
	s_waitcnt lgkmcnt(0)
	s_barrier
	s_waitcnt lgkmcnt(0)
	v_mfma_f32_16x16x32_bf16 v[62:65], v[144:147], v[178:181], v[62:65]
	v_mfma_f32_16x16x32_bf16 v[62:65], v[148:151], v[182:185], v[62:65]
	v_mfma_f32_16x16x32_bf16 v[58:61], v[158:161], v[182:185], v[58:61]
	v_mfma_f32_16x16x32_bf16 v[58:61], v[154:157], v[178:181], v[58:61]
	v_mfma_f32_16x16x32_bf16 v[54:57], v[162:165], v[178:181], v[54:57]
	v_mfma_f32_16x16x32_bf16 v[54:57], v[166:169], v[182:185], v[54:57]
	v_mfma_f32_16x16x32_bf16 v[50:53], v[174:177], v[182:185], v[50:53]
	v_mfma_f32_16x16x32_bf16 v[50:53], v[170:173], v[178:181], v[50:53]
	v_mfma_f32_16x16x32_bf16 v[34:37], v[170:173], v[186:189], v[34:37]
	v_mfma_f32_16x16x32_bf16 v[34:37], v[174:177], v[190:193], v[34:37]
	v_mfma_f32_16x16x32_bf16 v[38:41], v[166:169], v[190:193], v[38:41]
	v_mfma_f32_16x16x32_bf16 v[38:41], v[162:165], v[186:189], v[38:41]
	v_mfma_f32_16x16x32_bf16 v[42:45], v[154:157], v[186:189], v[42:45]
	v_mfma_f32_16x16x32_bf16 v[42:45], v[158:161], v[190:193], v[42:45]
	v_mfma_f32_16x16x32_bf16 v[46:49], v[148:151], v[190:193], v[46:49]
	v_mfma_f32_16x16x32_bf16 v[46:49], v[144:147], v[186:189], v[46:49]
	v_mfma_f32_16x16x32_bf16 v[30:33], v[144:147], v[204:207], v[30:33]
	v_mfma_f32_16x16x32_bf16 v[30:33], v[148:151], v[208:211], v[30:33]
	v_mfma_f32_16x16x32_bf16 v[26:29], v[158:161], v[208:211], v[26:29]
	v_mfma_f32_16x16x32_bf16 v[26:29], v[154:157], v[204:207], v[26:29]
	v_mfma_f32_16x16x32_bf16 v[22:25], v[162:165], v[204:207], v[22:25]
	v_mfma_f32_16x16x32_bf16 v[22:25], v[166:169], v[208:211], v[22:25]
	v_mfma_f32_16x16x32_bf16 v[18:21], v[174:177], v[208:211], v[18:21]
	v_mfma_f32_16x16x32_bf16 v[18:21], v[170:173], v[204:207], v[18:21]
	v_mfma_f32_16x16x32_bf16 v[2:5], v[170:173], v[212:215], v[2:5]
	v_mfma_f32_16x16x32_bf16 v[2:5], v[174:177], v[216:219], v[2:5]
	v_mfma_f32_16x16x32_bf16 v[6:9], v[166:169], v[216:219], v[6:9]
	v_mfma_f32_16x16x32_bf16 v[6:9], v[162:165], v[212:215], v[6:9]
	v_mfma_f32_16x16x32_bf16 v[10:13], v[154:157], v[212:215], v[10:13]
	v_mfma_f32_16x16x32_bf16 v[10:13], v[158:161], v[216:219], v[10:13]
	v_mfma_f32_16x16x32_bf16 v[14:17], v[148:151], v[216:219], v[14:17]
	v_mfma_f32_16x16x32_bf16 v[14:17], v[144:147], v[212:215], v[14:17]
	s_barrier
	s_add_i32 s76, s76, 2
	s_add_u32 s62, s62, 0x100
	s_addc_u32 s63, s63, 0
	s_add_u32 s53, s53, 0x100
	s_addc_u32 s58, s58, 0
	s_cmp_gt_u32 s76, 29
	s_cbranch_scc1 .LBB0_584

.LBB0_645:
	s_add_u32 s64, s8, 0x100
	s_addc_u32 s65, s9, 0
	s_and_b64 s[0:1], s[70:71], exec
	s_cselect_b32 s77, s63, s65
	s_cselect_b32 s76, s62, s64
	s_cselect_b32 s71, s85, s23
	s_cselect_b32 s70, s84, s7
	s_add_i32 s0, 0, 0x10000
	s_add_i32 s18, 0, 0x14000
	v_add_u32_e32 v106, s0, v1
	v_add_u32_e32 v154, s18, v1
	ds_read_b128 v[70:73], v106
	ds_read_b128 v[82:85], v106 offset:1024
	ds_read_b128 v[94:97], v106 offset:2048
	ds_read_b128 v[106:109], v106 offset:3072
	ds_read_b128 v[118:121], v154
	ds_read_b128 v[130:133], v154 offset:1024
	ds_read_b128 v[142:145], v154 offset:2048
	ds_read_b128 v[154:157], v154 offset:3072
	s_add_i32 m0, s29, 0xc000
	ds_read_b128 v[158:161], v237
	ds_read_b128 v[170:173], v237 offset:1024
	ds_read_b128 v[174:177], v237 offset:2048
	ds_read_b128 v[178:181], v237 offset:3072
	ds_read_b128 v[182:185], v237 offset:4096
	ds_read_b128 v[186:189], v237 offset:5120
	ds_read_b128 v[210:213], v237 offset:6144
	ds_read_b128 v[214:217], v237 offset:7168
	global_load_lds_dwordx4 v206, s[8:9]
	s_add_i32 m0, s29, 0xe000
	s_nop 0
	global_load_lds_dwordx4 v208, s[8:9]
	s_waitcnt vmcnt(8)
	s_waitcnt lgkmcnt(0)
	s_nop 0
	s_barrier
	s_waitcnt lgkmcnt(0)
	v_mfma_f32_16x16x32_bf16 v[166:169], v[70:73], v[158:161], v[166:169]
	v_mfma_f32_16x16x32_bf16 v[166:169], v[82:85], v[170:173], v[166:169]
	v_mfma_f32_16x16x32_bf16 v[162:165], v[106:109], v[170:173], v[162:165]
	v_mfma_f32_16x16x32_bf16 v[162:165], v[94:97], v[158:161], v[162:165]
	v_mfma_f32_16x16x32_bf16 v[150:153], v[118:121], v[158:161], v[150:153]
	v_mfma_f32_16x16x32_bf16 v[150:153], v[130:133], v[170:173], v[150:153]
	v_mfma_f32_16x16x32_bf16 v[146:149], v[154:157], v[170:173], v[146:149]
	v_mfma_f32_16x16x32_bf16 v[146:149], v[142:145], v[158:161], v[146:149]
	v_mfma_f32_16x16x32_bf16 v[122:125], v[142:145], v[174:177], v[122:125]
	v_mfma_f32_16x16x32_bf16 v[122:125], v[154:157], v[178:181], v[122:125]
	v_mfma_f32_16x16x32_bf16 v[126:129], v[130:133], v[178:181], v[126:129]
	v_mfma_f32_16x16x32_bf16 v[126:129], v[118:121], v[174:177], v[126:129]
	v_mfma_f32_16x16x32_bf16 v[134:137], v[94:97], v[174:177], v[134:137]
	v_mfma_f32_16x16x32_bf16 v[134:137], v[106:109], v[178:181], v[134:137]
	v_mfma_f32_16x16x32_bf16 v[138:141], v[82:85], v[178:181], v[138:141]
	v_mfma_f32_16x16x32_bf16 v[138:141], v[70:73], v[174:177], v[138:141]
	v_mfma_f32_16x16x32_bf16 v[114:117], v[70:73], v[182:185], v[114:117]
	v_mfma_f32_16x16x32_bf16 v[114:117], v[82:85], v[186:189], v[114:117]
	v_mfma_f32_16x16x32_bf16 v[110:113], v[106:109], v[186:189], v[110:113]
	v_mfma_f32_16x16x32_bf16 v[110:113], v[94:97], v[182:185], v[110:113]
	v_mfma_f32_16x16x32_bf16 v[102:105], v[118:121], v[182:185], v[102:105]
	v_mfma_f32_16x16x32_bf16 v[102:105], v[130:133], v[186:189], v[102:105]
	v_mfma_f32_16x16x32_bf16 v[98:101], v[154:157], v[186:189], v[98:101]
	v_mfma_f32_16x16x32_bf16 v[98:101], v[142:145], v[182:185], v[98:101]
	v_mfma_f32_16x16x32_bf16 v[74:77], v[142:145], v[210:213], v[74:77]
	v_mfma_f32_16x16x32_bf16 v[74:77], v[154:157], v[214:217], v[74:77]
	v_mfma_f32_16x16x32_bf16 v[78:81], v[130:133], v[214:217], v[78:81]
	v_mfma_f32_16x16x32_bf16 v[78:81], v[118:121], v[210:213], v[78:81]
	v_mfma_f32_16x16x32_bf16 v[86:89], v[94:97], v[210:213], v[86:89]
	v_mfma_f32_16x16x32_bf16 v[86:89], v[106:109], v[214:217], v[86:89]
	v_mfma_f32_16x16x32_bf16 v[90:93], v[82:85], v[214:217], v[90:93]
	v_mfma_f32_16x16x32_bf16 v[90:93], v[70:73], v[210:213], v[90:93]
	s_barrier
	s_add_i32 s0, s0, s28
	s_mov_b32 m0, s0
	ds_read_b128 v[158:161], v237 offset:16384
	ds_read_b128 v[170:173], v237 offset:17408
	ds_read_b128 v[174:177], v237 offset:18432
	ds_read_b128 v[178:181], v237 offset:19456
	ds_read_b128 v[182:185], v237 offset:20480
	ds_read_b128 v[186:189], v237 offset:21504
	ds_read_b128 v[210:213], v237 offset:22528
	ds_read_b128 v[214:217], v237 offset:23552
	global_load_lds_dwordx4 v192, s[70:71]
	s_add_i32 m0, s0, 0x2000
	s_add_u32 s0, s70, 0x160000
	s_addc_u32 s1, s71, 0
	s_add_i32 s8, s18, s28
	global_load_lds_dwordx4 v190, s[70:71]
	s_mov_b32 m0, s8
	s_nop 0
	global_load_lds_dwordx4 v192, s[0:1]
	s_add_i32 m0, s8, 0x2000
	s_nop 0
	global_load_lds_dwordx4 v190, s[0:1]
	s_mov_b32 m0, s29
	s_nop 0
	global_load_lds_dwordx4 v192, s[76:77]
	s_mov_b32 m0, s31
	s_nop 0
	global_load_lds_dwordx4 v190, s[76:77]
	s_waitcnt vmcnt(8)
	s_waitcnt lgkmcnt(0)
	s_barrier
	s_waitcnt lgkmcnt(0)
	v_mfma_f32_16x16x32_bf16 v[62:65], v[70:73], v[158:161], v[62:65]
	v_mfma_f32_16x16x32_bf16 v[62:65], v[82:85], v[170:173], v[62:65]
	v_mfma_f32_16x16x32_bf16 v[58:61], v[106:109], v[170:173], v[58:61]
	v_mfma_f32_16x16x32_bf16 v[58:61], v[94:97], v[158:161], v[58:61]
	v_mfma_f32_16x16x32_bf16 v[54:57], v[118:121], v[158:161], v[54:57]
	v_mfma_f32_16x16x32_bf16 v[54:57], v[130:133], v[170:173], v[54:57]
	v_mfma_f32_16x16x32_bf16 v[50:53], v[154:157], v[170:173], v[50:53]
	v_mfma_f32_16x16x32_bf16 v[50:53], v[142:145], v[158:161], v[50:53]
	v_mfma_f32_16x16x32_bf16 v[34:37], v[142:145], v[174:177], v[34:37]
	v_mfma_f32_16x16x32_bf16 v[34:37], v[154:157], v[178:181], v[34:37]
	v_mfma_f32_16x16x32_bf16 v[38:41], v[130:133], v[178:181], v[38:41]
	v_mfma_f32_16x16x32_bf16 v[38:41], v[118:121], v[174:177], v[38:41]
	v_mfma_f32_16x16x32_bf16 v[42:45], v[94:97], v[174:177], v[42:45]
	v_mfma_f32_16x16x32_bf16 v[42:45], v[106:109], v[178:181], v[42:45]
	v_mfma_f32_16x16x32_bf16 v[46:49], v[82:85], v[178:181], v[46:49]
	v_mfma_f32_16x16x32_bf16 v[46:49], v[70:73], v[174:177], v[46:49]
	v_mfma_f32_16x16x32_bf16 v[30:33], v[70:73], v[182:185], v[30:33]
	v_mfma_f32_16x16x32_bf16 v[30:33], v[82:85], v[186:189], v[30:33]
	v_mfma_f32_16x16x32_bf16 v[26:29], v[106:109], v[186:189], v[26:29]
	v_mfma_f32_16x16x32_bf16 v[26:29], v[94:97], v[182:185], v[26:29]
	v_mfma_f32_16x16x32_bf16 v[22:25], v[118:121], v[182:185], v[22:25]
	v_mfma_f32_16x16x32_bf16 v[22:25], v[130:133], v[186:189], v[22:25]
	v_mfma_f32_16x16x32_bf16 v[18:21], v[154:157], v[186:189], v[18:21]
	v_mfma_f32_16x16x32_bf16 v[18:21], v[142:145], v[182:185], v[18:21]
	v_mfma_f32_16x16x32_bf16 v[2:5], v[142:145], v[210:213], v[2:5]
	v_mfma_f32_16x16x32_bf16 v[2:5], v[154:157], v[214:217], v[2:5]
	v_mfma_f32_16x16x32_bf16 v[6:9], v[130:133], v[214:217], v[6:9]
	v_mfma_f32_16x16x32_bf16 v[6:9], v[118:121], v[210:213], v[6:9]
	v_mfma_f32_16x16x32_bf16 v[10:13], v[94:97], v[210:213], v[10:13]
	v_mfma_f32_16x16x32_bf16 v[10:13], v[106:109], v[214:217], v[10:13]
	v_mfma_f32_16x16x32_bf16 v[14:17], v[82:85], v[214:217], v[14:17]
	v_mfma_f32_16x16x32_bf16 v[14:17], v[70:73], v[210:213], v[14:17]
	s_barrier
	s_add_i32 s8, 0, 0x18000
	s_add_i32 s9, 0, 0x1c000
	v_add_u32_e32 v106, s8, v1
	v_add_u32_e32 v154, s9, v1
	ds_read_b128 v[70:73], v106
	ds_read_b128 v[82:85], v106 offset:1024
	ds_read_b128 v[94:97], v106 offset:2048
	ds_read_b128 v[106:109], v106 offset:3072
	ds_read_b128 v[118:121], v154
	ds_read_b128 v[130:133], v154 offset:1024
	ds_read_b128 v[142:145], v154 offset:2048
	ds_read_b128 v[154:157], v154 offset:3072
	s_add_u32 s0, s76, 0x160000
	s_addc_u32 s1, s77, 0
	s_mov_b32 m0, s33
	ds_read_b128 v[158:161], v237 offset:32768
	ds_read_b128 v[170:173], v237 offset:33792
	ds_read_b128 v[174:177], v237 offset:34816
	ds_read_b128 v[178:181], v237 offset:35840
	ds_read_b128 v[182:185], v237 offset:36864
	ds_read_b128 v[186:189], v237 offset:37888
	ds_read_b128 v[210:213], v237 offset:38912
	ds_read_b128 v[214:217], v237 offset:39936
	global_load_lds_dwordx4 v192, s[0:1]
	s_mov_b32 m0, s43
	s_nop 0
	global_load_lds_dwordx4 v190, s[0:1]
	s_waitcnt vmcnt(8)
	s_waitcnt lgkmcnt(0)
	s_nop 0
	s_barrier
	s_waitcnt lgkmcnt(0)
	v_mfma_f32_16x16x32_bf16 v[166:169], v[70:73], v[158:161], v[166:169]
	v_mfma_f32_16x16x32_bf16 v[166:169], v[82:85], v[170:173], v[166:169]
	v_mfma_f32_16x16x32_bf16 v[162:165], v[106:109], v[170:173], v[162:165]
	v_mfma_f32_16x16x32_bf16 v[162:165], v[94:97], v[158:161], v[162:165]
	v_mfma_f32_16x16x32_bf16 v[150:153], v[118:121], v[158:161], v[150:153]
	v_mfma_f32_16x16x32_bf16 v[150:153], v[130:133], v[170:173], v[150:153]
	v_mfma_f32_16x16x32_bf16 v[146:149], v[154:157], v[170:173], v[146:149]
	v_mfma_f32_16x16x32_bf16 v[146:149], v[142:145], v[158:161], v[146:149]
	v_mfma_f32_16x16x32_bf16 v[122:125], v[142:145], v[174:177], v[122:125]
	v_mfma_f32_16x16x32_bf16 v[122:125], v[154:157], v[178:181], v[122:125]
	v_mfma_f32_16x16x32_bf16 v[126:129], v[130:133], v[178:181], v[126:129]
	v_mfma_f32_16x16x32_bf16 v[126:129], v[118:121], v[174:177], v[126:129]
	v_mfma_f32_16x16x32_bf16 v[134:137], v[94:97], v[174:177], v[134:137]
	v_mfma_f32_16x16x32_bf16 v[134:137], v[106:109], v[178:181], v[134:137]
	v_mfma_f32_16x16x32_bf16 v[138:141], v[82:85], v[178:181], v[138:141]
	v_mfma_f32_16x16x32_bf16 v[138:141], v[70:73], v[174:177], v[138:141]
	v_mfma_f32_16x16x32_bf16 v[114:117], v[70:73], v[182:185], v[114:117]
	v_mfma_f32_16x16x32_bf16 v[114:117], v[82:85], v[186:189], v[114:117]
	v_mfma_f32_16x16x32_bf16 v[110:113], v[106:109], v[186:189], v[110:113]
	v_mfma_f32_16x16x32_bf16 v[110:113], v[94:97], v[182:185], v[110:113]
	v_mfma_f32_16x16x32_bf16 v[102:105], v[118:121], v[182:185], v[102:105]
	v_mfma_f32_16x16x32_bf16 v[102:105], v[130:133], v[186:189], v[102:105]
	v_mfma_f32_16x16x32_bf16 v[98:101], v[154:157], v[186:189], v[98:101]
	v_mfma_f32_16x16x32_bf16 v[98:101], v[142:145], v[182:185], v[98:101]
	v_mfma_f32_16x16x32_bf16 v[74:77], v[142:145], v[210:213], v[74:77]
	v_mfma_f32_16x16x32_bf16 v[74:77], v[154:157], v[214:217], v[74:77]
	v_mfma_f32_16x16x32_bf16 v[78:81], v[130:133], v[214:217], v[78:81]
	v_mfma_f32_16x16x32_bf16 v[78:81], v[118:121], v[210:213], v[78:81]
	v_mfma_f32_16x16x32_bf16 v[86:89], v[94:97], v[210:213], v[86:89]
	v_mfma_f32_16x16x32_bf16 v[86:89], v[106:109], v[214:217], v[86:89]
	v_mfma_f32_16x16x32_bf16 v[90:93], v[82:85], v[214:217], v[90:93]
	v_mfma_f32_16x16x32_bf16 v[90:93], v[70:73], v[210:213], v[90:93]
	s_barrier
	s_add_u32 s98, s70, 0x80
	s_addc_u32 s99, s71, 0
	s_add_u32 s100, s76, 0x80
	s_addc_u32 s101, s77, 0
	s_add_i32 s0, s8, s28
	s_mov_b32 m0, s0
	ds_read_b128 v[158:161], v237 offset:49152
	ds_read_b128 v[170:173], v237 offset:50176
	ds_read_b128 v[174:177], v237 offset:51200
	ds_read_b128 v[178:181], v237 offset:52224
	ds_read_b128 v[182:185], v237 offset:53248
	ds_read_b128 v[186:189], v237 offset:54272
	ds_read_b128 v[210:213], v237 offset:55296
	ds_read_b128 v[214:217], v237 offset:56320
	global_load_lds_dwordx4 v192, s[98:99]
	s_add_i32 m0, s0, 0x2000
	s_add_u32 s0, s70, 0x160080
	s_addc_u32 s1, s71, 0
	s_add_i32 s8, s9, s28
	global_load_lds_dwordx4 v190, s[98:99]
	s_mov_b32 m0, s8
	s_nop 0
	global_load_lds_dwordx4 v192, s[0:1]
	s_add_i32 m0, s8, 0x2000
	s_nop 0
	global_load_lds_dwordx4 v190, s[0:1]
	s_mov_b32 m0, s68
	s_nop 0
	global_load_lds_dwordx4 v192, s[100:101]
	s_mov_b32 m0, s79
	s_nop 0
	global_load_lds_dwordx4 v190, s[100:101]
	s_waitcnt vmcnt(8)
	s_waitcnt lgkmcnt(0)
	s_barrier
	s_waitcnt lgkmcnt(0)
	v_mfma_f32_16x16x32_bf16 v[62:65], v[70:73], v[158:161], v[62:65]
	v_mfma_f32_16x16x32_bf16 v[62:65], v[82:85], v[170:173], v[62:65]
	v_mfma_f32_16x16x32_bf16 v[58:61], v[106:109], v[170:173], v[58:61]
	v_mfma_f32_16x16x32_bf16 v[58:61], v[94:97], v[158:161], v[58:61]
	v_mfma_f32_16x16x32_bf16 v[54:57], v[118:121], v[158:161], v[54:57]
	v_mfma_f32_16x16x32_bf16 v[54:57], v[130:133], v[170:173], v[54:57]
	v_mfma_f32_16x16x32_bf16 v[50:53], v[154:157], v[170:173], v[50:53]
	v_mfma_f32_16x16x32_bf16 v[50:53], v[142:145], v[158:161], v[50:53]
	v_mfma_f32_16x16x32_bf16 v[34:37], v[142:145], v[174:177], v[34:37]
	v_mfma_f32_16x16x32_bf16 v[34:37], v[154:157], v[178:181], v[34:37]
	v_mfma_f32_16x16x32_bf16 v[38:41], v[130:133], v[178:181], v[38:41]
	v_mfma_f32_16x16x32_bf16 v[38:41], v[118:121], v[174:177], v[38:41]
	v_mfma_f32_16x16x32_bf16 v[42:45], v[94:97], v[174:177], v[42:45]
	v_mfma_f32_16x16x32_bf16 v[42:45], v[106:109], v[178:181], v[42:45]
	v_mfma_f32_16x16x32_bf16 v[46:49], v[82:85], v[178:181], v[46:49]
	v_mfma_f32_16x16x32_bf16 v[46:49], v[70:73], v[174:177], v[46:49]
	v_mfma_f32_16x16x32_bf16 v[30:33], v[70:73], v[182:185], v[30:33]
	v_mfma_f32_16x16x32_bf16 v[30:33], v[82:85], v[186:189], v[30:33]
	v_mfma_f32_16x16x32_bf16 v[26:29], v[106:109], v[186:189], v[26:29]
	v_mfma_f32_16x16x32_bf16 v[26:29], v[94:97], v[182:185], v[26:29]
	v_mfma_f32_16x16x32_bf16 v[22:25], v[118:121], v[182:185], v[22:25]
	v_mfma_f32_16x16x32_bf16 v[22:25], v[130:133], v[186:189], v[22:25]
	v_mfma_f32_16x16x32_bf16 v[18:21], v[154:157], v[186:189], v[18:21]
	v_mfma_f32_16x16x32_bf16 v[18:21], v[142:145], v[182:185], v[18:21]
	v_mfma_f32_16x16x32_bf16 v[2:5], v[142:145], v[210:213], v[2:5]
	v_mfma_f32_16x16x32_bf16 v[2:5], v[154:157], v[214:217], v[2:5]
	v_mfma_f32_16x16x32_bf16 v[6:9], v[130:133], v[214:217], v[6:9]
	v_mfma_f32_16x16x32_bf16 v[6:9], v[118:121], v[210:213], v[6:9]
	v_mfma_f32_16x16x32_bf16 v[10:13], v[94:97], v[210:213], v[10:13]
	v_mfma_f32_16x16x32_bf16 v[10:13], v[106:109], v[214:217], v[10:13]
	v_mfma_f32_16x16x32_bf16 v[14:17], v[82:85], v[214:217], v[14:17]
	v_mfma_f32_16x16x32_bf16 v[14:17], v[70:73], v[210:213], v[14:17]
	s_barrier
	s_add_i32 s41, s41, 2
	s_add_u32 s7, s7, 0x100
	s_addc_u32 s23, s23, 0
	s_cmpk_gt_u32 s41, 0x55
	s_mov_b64 s[8:9], s[64:65]
	s_cbranch_scc1 .LBB0_648
